# gemm_in output-tile epilogue: 8-step LDS-read/wait/store ladder issued as 8 LDS reads up front then 8 stores behind counted lgkmcnt waits
# baseline (speedup 1.0000x reference)
; #define WAIT_V0() asm volatile("s_waitcnt vmcnt(0)" ::: "memory")
; DI int glds_row(int i) { const int tid = ltid(); return ((tid >> 6) * 4 + i) * 8 + ((tid & 63) >> 3); }
; DI int glds_chunk(int row) { return (ltid() & 7) ^ ((row >> 1) & 7); }
; DI void gemm_core(char* smem, int nk, const char* Ab, const char* Bb, const unsigned (&aoff)[4], const unsigned (&boff)[4],
;                   f32x16 (&acc)[2][2]) {
;     ...
;   auto stage = [&](int buf, int kt) __attribute__((always_inline)) {
;     const char* ak = Ab + kt * 128;
;     const char* bk = Bb + kt * 128;
;     char* sa = smem + buf * STAGE_B + w * 4096;
; #pragma unroll
;     for (int i = 0; i < 4; ++i) {
;       __builtin_amdgcn_global_load_lds((const unsigned*)(ak + aoff[i]), (unsigned*)(sa + i * 1024), 16, 0, 0);
;       __builtin_amdgcn_global_load_lds((const unsigned*)(bk + boff[i]), (unsigned*)(sa + 16384 + i * 1024), 16, 0, 0);
;     }
;   };
;   stage(0, 0);
;   WAIT_V0();
;   __syncthreads();
; DI void gemm_tile(char* smem, int nk, const bf16* A, int lda, int m0, const bf16* Bt, int ldb, int n0, f32x16 (&acc)[2][2]) {
;   unsigned aoff[4], boff[4];
; #pragma unroll
;   for (int i = 0; i < 4; ++i) {
;     const int row = glds_row(i), ch = glds_chunk(row);
;     aoff[i] = (unsigned)((row * lda + ch * 8) * 2);
;     boff[i] = (unsigned)((row * ldb + ch * 8) * 2);
;   }
;   gemm_core(smem, nk, (const char*)(A + (size_t)m0 * lda), (const char*)(Bt + (size_t)n0 * ldb), aoff, boff, acc);
.LBB0_436:
	v_mov_b32_e32 v0, v161
	s_ashr_i32 s0, s14, 3
	v_lshrrev_b32_e32 v1, 1, v0
	v_lshrrev_b32_e32 v2, 3, v0
	v_bfe_u32 v0, v0, 3, 3
	v_and_or_b32 v0, v1, s9, v0
	v_mov_b32_e32 v1, v161
	v_bfe_u32 v2, v2, 1, 2
	v_xor_b32_e32 v1, v2, v1
	v_lshlrev_b32_e32 v0, 11, v0
	v_lshlrev_b32_e32 v1, 4, v1
	v_and_or_b32 v136, v1, s92, v0
	v_mov_b32_e32 v0, v161
	s_and_b32 s1, s0, 0xffffffc0
	v_ashrrev_i32_e32 v1, 1, v0
	v_and_b32_e32 v1, 0xffffffe0, v1
	v_bfe_u32 v0, v0, 3, 3
	v_or3_b32 v0, v0, v1, 8
	v_mov_b32_e32 v1, v161
	v_lshrrev_b32_e32 v2, 1, v0
	v_xor_b32_e32 v1, v2, v1
	v_lshlrev_b32_e32 v0, 11, v0
	v_lshlrev_b32_e32 v1, 4, v1
	v_and_or_b32 v0, v1, s92, v0
	v_mov_b32_e32 v1, v161
	s_lshl_b32 s10, s0, 1
	v_lshrrev_b32_e32 v2, 1, v1
	v_lshrrev_b32_e32 v3, 3, v1
	v_bfe_u32 v1, v1, 3, 3
	v_and_or_b32 v1, v2, s9, v1
	v_mov_b32_e32 v2, v161
	s_bfe_u32 s11, s0, 0x10005
	v_bfe_u32 v3, v3, 1, 2
	s_and_b32 s10, s10, 62
	s_or_b32 s1, s11, s1
	v_xor_b32_e32 v2, v3, v2
	s_or_b32 s1, s1, s10
	s_or_b32 s10, s0, 63
	v_lshlrev_b32_e32 v2, 4, v2
	s_cmpk_lt_i32 s10, 0x2c0
	v_lshlrev_b32_e32 v1, 11, v1
	v_and_b32_e32 v2, 0x70, v2
	s_cselect_b32 s1, s1, s0
	v_or3_b32 v2, v1, v2, s8
	v_mov_b32_e32 v1, v161
	s_mul_hi_i32 s10, s1, 0x2e8ba2e9
	s_lshr_b32 s11, s10, 31
	v_ashrrev_i32_e32 v3, 1, v1
	s_ashr_i32 s10, s10, 1
	v_and_b32_e32 v3, 0xffffffe0, v3
	v_bfe_u32 v1, v1, 3, 3
	s_and_b32 s0, s13, 0xc0
	s_add_i32 s10, s10, s11
	v_or3_b32 v1, v1, v3, 24
	v_mov_b32_e32 v3, v161
	s_add_i32 s15, s10, s0
	s_bfe_i32 s11, s14, 0x10002
	s_mul_i32 s10, s10, 11
	v_lshrrev_b32_e32 v4, 1, v1
	s_and_b32 s11, s11, 11
	s_sub_i32 s1, s1, s10
	v_xor_b32_e32 v3, v4, v3
	s_lshl_b32 s0, s15, 7
	s_add_i32 s1, s1, s11
	v_lshlrev_b32_e32 v1, 11, v1
	v_lshlrev_b32_e32 v3, 4, v3
	v_mov_b32_e32 v12, v161
	s_lshl_b32 s10, s1, 7
	v_and_or_b32 v4, v3, s92, v1
	s_ashr_i32 s1, s0, 31
	s_lshl_b64 s[16:17], s[0:1], 11
	v_and_b32_e32 v1, 31, v12
	v_lshrrev_b32_e32 v5, 1, v12
	v_and_or_b32 v1, v5, s6, v1
	s_add_u32 s16, s84, s16
	v_lshlrev_b32_e32 v112, 7, v1
	v_lshlrev_b32_e32 v1, 6, v12
	s_addc_u32 s17, s85, s17
	s_ashr_i32 s11, s10, 31
	v_and_b32_e32 v89, 0xfffff000, v1
	s_lshl_b64 s[18:19], s[10:11], 11
	v_add_u32_e32 v88, 0x4000, v89
	v_readfirstlane_b32 s20, v89
	s_add_u32 s18, s2, s18
	s_mov_b32 m0, s20
	v_readfirstlane_b32 s21, v88
	v_or_b32_e32 v90, 0x400, v89
	s_addc_u32 s19, s12, s19
	global_load_lds_dwordx4 v136, s[16:17]
	s_mov_b32 m0, s21
	v_readfirstlane_b32 s22, v90
	v_add_u32_e32 v91, 0x4400, v89
	global_load_lds_dwordx4 v136, s[18:19]
	s_mov_b32 m0, s22
	v_readfirstlane_b32 s23, v91
	v_or_b32_e32 v92, 0x800, v89
	global_load_lds_dwordx4 v0, s[16:17]
	s_mov_b32 m0, s23
	v_readfirstlane_b32 s28, v92
	v_add_u32_e32 v93, 0x4800, v89
	global_load_lds_dwordx4 v0, s[18:19]
	s_mov_b32 m0, s28
	v_readfirstlane_b32 s29, v93
	v_or_b32_e32 v94, 0xc00, v89
	global_load_lds_dwordx4 v2, s[16:17]
	s_mov_b32 m0, s29
	v_readfirstlane_b32 s40, v94
	v_add_u32_e32 v95, 0x4c00, v89
	v_lshrrev_b32_e32 v3, 5, v12
	v_bfe_u32 v99, v12, 1, 3
	global_load_lds_dwordx4 v2, s[18:19]
	s_mov_b32 m0, s40
	v_readfirstlane_b32 s41, v95
	v_add_u32_e32 v97, 0x8000, v89
	v_bitop3_b32 v3, v3, v99, 1 bitop3:0x6c
	v_lshl_add_u64 v[64:65], s[16:17], 0, v[136:137]
	v_mov_b32_e32 v1, v137
	global_load_lds_dwordx4 v4, s[16:17]
	s_mov_b32 m0, s41
	v_add_u32_e32 v96, 0xc000, v89
	v_readfirstlane_b32 s42, v97
	v_lshlrev_b32_e32 v6, 4, v3
	v_lshl_add_u64 v[66:67], s[18:19], 0, v[136:137]
	v_lshl_add_u64 v[68:69], s[16:17], 0, v[0:1]
	v_lshl_add_u64 v[70:71], s[18:19], 0, v[0:1]
	v_mov_b32_e32 v3, v137
	global_load_lds_dwordx4 v4, s[18:19]
	v_lshl_add_u64 v[0:1], v[64:65], 0, s[94:95]
	s_mov_b32 m0, s42
	v_readfirstlane_b32 s43, v96
	v_add_u32_e32 v98, 0x8400, v89
	v_lshl_add_u64 v[72:73], s[16:17], 0, v[2:3]
	v_lshl_add_u64 v[74:75], s[18:19], 0, v[2:3]
	global_load_lds_dwordx4 v[0:1], off
	v_lshl_add_u64 v[0:1], v[66:67], 0, s[94:95]
	s_mov_b32 m0, s43
	v_readfirstlane_b32 s44, v98
	v_add_u32_e32 v2, 0xc400, v89
	v_mov_b32_e32 v5, v137
	global_load_lds_dwordx4 v[0:1], off
	v_lshl_add_u64 v[0:1], v[68:69], 0, s[94:95]
	s_mov_b32 m0, s44
	v_readfirstlane_b32 s1, v2
	v_add_u32_e32 v2, 0x8800, v89
	v_lshl_add_u64 v[76:77], s[16:17], 0, v[4:5]
	global_load_lds_dwordx4 v[0:1], off
	v_lshl_add_u64 v[0:1], v[70:71], 0, s[94:95]
	s_mov_b32 m0, s1
	v_readfirstlane_b32 s16, v2
	v_add_u32_e32 v2, 0xc800, v89
	global_load_lds_dwordx4 v[0:1], off
	v_lshl_add_u64 v[0:1], v[72:73], 0, s[94:95]
	s_mov_b32 m0, s16
	v_readfirstlane_b32 s17, v2
	v_add_u32_e32 v2, 0x8c00, v89
	v_lshl_add_u64 v[78:79], s[18:19], 0, v[4:5]
	global_load_lds_dwordx4 v[0:1], off
	v_lshl_add_u64 v[0:1], v[74:75], 0, s[94:95]
	s_mov_b32 m0, s17
	v_readfirstlane_b32 s18, v2
	v_add_u32_e32 v2, 0xcc00, v89
	global_load_lds_dwordx4 v[0:1], off
	v_lshl_add_u64 v[0:1], v[76:77], 0, s[94:95]
	s_mov_b32 m0, s18
	v_readfirstlane_b32 s19, v2
	global_load_lds_dwordx4 v[0:1], off
	v_lshl_add_u64 v[0:1], v[78:79], 0, s[94:95]
	s_mov_b32 m0, s19
	v_or_b32_e32 v80, v112, v6
	global_load_lds_dwordx4 v[0:1], off
	s_waitcnt vmcnt(8)
	s_waitcnt vmcnt(8) lgkmcnt(0)
	s_barrier
; #define WAIT_V0() asm volatile("s_waitcnt vmcnt(0)" ::: "memory")
; DI void gemm_core(char* smem, int nk, const char* Ab, const char* Bb, const unsigned (&aoff)[4], const unsigned (&boff)[4],
;                   f32x16 (&acc)[2][2]) {
;     ...
;   for (int kt = 0; kt < nk; ++kt) {
;     const int cur = kt & 1;
;     if (kt + 1 < nk) stage(cur ^ 1, kt + 1);
;     const char* sb = smem + cur * STAGE_B;
; #pragma unroll
;     for (int ks = 0; ks < 4; ++ks) {
;       bf16x8 af[2], bfr[2];
; #pragma unroll
;       for (int mb = 0; mb < 2; ++mb) af[mb] = *(const bf16x8*)(sb + a_base + mb * 4096 + xo[ks]);
; #pragma unroll
;       for (int nb = 0; nb < 2; ++nb) bfr[nb] = *(const bf16x8*)(sb + b_base + nb * 4096 + xo[ks]);
; #pragma unroll
;       for (int mb = 0; mb < 2; ++mb)
; #pragma unroll
;         for (int nb = 0; nb < 2; ++nb)
;           acc[mb][nb] = __builtin_amdgcn_mfma_f32_32x32x16_bf16(af[mb], bfr[nb], acc[mb][nb], 0, 0, 0);
;     }
;     WAIT_V0();
;     __syncthreads();
;   }
	ds_read_b128 v[0:3], v80
	v_lshlrev_b32_e32 v4, 7, v12
	v_and_b32_e32 v113, 0x2f80, v4
	v_or_b32_e32 v82, v113, v6
	ds_read_b128 v[4:7], v82 offset:16384
	ds_read_b128 v[8:11], v82 offset:20480
	s_waitcnt lgkmcnt(0)
	v_mfma_f32_32x32x16_bf16 v[48:63], v[0:3], v[4:7], 0
	v_bfe_u32 v114, v12, 5, 1
	s_mov_b32 m0, s20
	v_mfma_f32_32x32x16_bf16 v[32:47], v[0:3], v[8:11], 0
	ds_read_b128 v[0:3], v80 offset:4096
	s_waitcnt lgkmcnt(0)
	v_mfma_f32_32x32x16_bf16 v[16:31], v[0:3], v[4:7], 0
	v_bitop3_b32 v4, v114, v99, 2 bitop3:0x36
	v_lshlrev_b32_e32 v83, 4, v4
	v_or_b32_e32 v81, v112, v83
	ds_read_b128 v[84:87], v81
	v_or_b32_e32 v83, v113, v83
	ds_read_b128 v[100:103], v83 offset:16384
	ds_read_b128 v[104:107], v83 offset:20480
	s_waitcnt lgkmcnt(0)
	v_mfma_f32_32x32x16_bf16 v[48:63], v[84:87], v[100:103], v[48:63]
	v_mfma_f32_32x32x16_bf16 v[32:47], v[84:87], v[104:107], v[32:47]
	ds_read_b128 v[84:87], v81 offset:4096
	v_mfma_f32_32x32x16_bf16 v[0:15], v[0:3], v[8:11], 0
	s_waitcnt lgkmcnt(0)
	v_mfma_f32_32x32x16_bf16 v[16:31], v[84:87], v[100:103], v[16:31]
	v_bitop3_b32 v100, v114, v99, 4 bitop3:0x36
	v_lshlrev_b32_e32 v108, 4, v100
	v_mfma_f32_32x32x16_bf16 v[0:15], v[84:87], v[104:107], v[0:15]
	v_or_b32_e32 v84, v112, v108
	ds_read_b128 v[100:103], v84
	v_or_b32_e32 v85, v113, v108
	ds_read_b128 v[104:107], v85 offset:16384
	ds_read_b128 v[108:111], v85 offset:20480
	v_bitop3_b32 v86, v114, v99, 6 bitop3:0x36
	v_lshlrev_b32_e32 v87, 4, v86
	s_waitcnt lgkmcnt(0)
	v_mfma_f32_32x32x16_bf16 v[48:63], v[100:103], v[104:107], v[48:63]
	v_or_b32_e32 v86, v112, v87
	v_or_b32_e32 v87, v113, v87
	v_mfma_f32_32x32x16_bf16 v[32:47], v[100:103], v[108:111], v[32:47]
	ds_read_b128 v[100:103], v84 offset:4096
	s_waitcnt lgkmcnt(0)
	v_mfma_f32_32x32x16_bf16 v[16:31], v[100:103], v[104:107], v[16:31]
	ds_read_b128 v[104:107], v87 offset:16384
	v_mfma_f32_32x32x16_bf16 v[0:15], v[100:103], v[108:111], v[0:15]
	ds_read_b128 v[100:103], v86
	ds_read_b128 v[108:111], v87 offset:20480
	ds_read_b128 v[120:123], v86 offset:4096
	s_waitcnt vmcnt(0)
	s_waitcnt vmcnt(0) lgkmcnt(0)
	s_barrier
	v_mfma_f32_32x32x16_bf16 v[48:63], v[100:103], v[104:107], v[48:63]
	v_mfma_f32_32x32x16_bf16 v[32:47], v[100:103], v[108:111], v[32:47]
	v_mfma_f32_32x32x16_bf16 v[16:31], v[120:123], v[104:107], v[16:31]
	v_mfma_f32_32x32x16_bf16 v[0:15], v[120:123], v[108:111], v[0:15]
	ds_read_b128 v[100:103], v80 offset:32768
	ds_read_b128 v[104:107], v82 offset:49152
	ds_read_b128 v[108:111], v82 offset:53248
	v_lshl_add_u64 v[116:117], v[64:65], 0, s[36:37]
	global_load_lds_dwordx4 v[116:117], off
	v_lshl_add_u64 v[118:119], v[66:67], 0, s[36:37]
	s_mov_b32 m0, s21
	s_nop 0
	global_load_lds_dwordx4 v[118:119], off
	v_lshl_add_u64 v[116:117], v[68:69], 0, s[36:37]
	s_mov_b32 m0, s22
	s_nop 0
	global_load_lds_dwordx4 v[116:117], off
	v_lshl_add_u64 v[118:119], v[70:71], 0, s[36:37]
	s_mov_b32 m0, s23
	s_nop 0
	global_load_lds_dwordx4 v[118:119], off
	v_lshl_add_u64 v[116:117], v[72:73], 0, s[36:37]
	s_mov_b32 m0, s28
	s_nop 0
	global_load_lds_dwordx4 v[116:117], off
	v_lshl_add_u64 v[118:119], v[74:75], 0, s[36:37]
	s_mov_b32 m0, s29
	s_nop 0
	global_load_lds_dwordx4 v[118:119], off
	v_lshl_add_u64 v[116:117], v[76:77], 0, s[36:37]
	s_mov_b32 m0, s40
	s_nop 0
	global_load_lds_dwordx4 v[116:117], off
	v_lshl_add_u64 v[118:119], v[78:79], 0, s[36:37]
	s_mov_b32 m0, s41
	s_nop 0
	global_load_lds_dwordx4 v[118:119], off
	s_waitcnt lgkmcnt(0)
	v_mfma_f32_32x32x16_bf16 v[48:63], v[100:103], v[104:107], v[48:63]
	s_mov_b32 m0, s42
	v_mfma_f32_32x32x16_bf16 v[32:47], v[100:103], v[108:111], v[32:47]
	ds_read_b128 v[100:103], v80 offset:36864
	s_waitcnt lgkmcnt(0)
	v_mfma_f32_32x32x16_bf16 v[16:31], v[100:103], v[104:107], v[16:31]
	v_mfma_f32_32x32x16_bf16 v[0:15], v[100:103], v[108:111], v[0:15]
	ds_read_b128 v[100:103], v81 offset:32768
	ds_read_b128 v[104:107], v83 offset:49152
	ds_read_b128 v[108:111], v83 offset:53248
	s_waitcnt lgkmcnt(0)
	v_mfma_f32_32x32x16_bf16 v[48:63], v[100:103], v[104:107], v[48:63]
	v_mfma_f32_32x32x16_bf16 v[32:47], v[100:103], v[108:111], v[32:47]
	ds_read_b128 v[100:103], v81 offset:36864
	s_waitcnt lgkmcnt(0)
	v_mfma_f32_32x32x16_bf16 v[16:31], v[100:103], v[104:107], v[16:31]
	v_mfma_f32_32x32x16_bf16 v[0:15], v[100:103], v[108:111], v[0:15]
	ds_read_b128 v[100:103], v84 offset:32768
	ds_read_b128 v[104:107], v85 offset:49152
	ds_read_b128 v[108:111], v85 offset:53248
	s_waitcnt lgkmcnt(0)
	v_mfma_f32_32x32x16_bf16 v[48:63], v[100:103], v[104:107], v[48:63]
	v_mfma_f32_32x32x16_bf16 v[32:47], v[100:103], v[108:111], v[32:47]
	ds_read_b128 v[100:103], v84 offset:36864
	s_waitcnt lgkmcnt(0)
	v_mfma_f32_32x32x16_bf16 v[16:31], v[100:103], v[104:107], v[16:31]
	v_mfma_f32_32x32x16_bf16 v[0:15], v[100:103], v[108:111], v[0:15]
	ds_read_b128 v[100:103], v86 offset:32768
	ds_read_b128 v[104:107], v87 offset:49152
	ds_read_b128 v[108:111], v87 offset:53248
	ds_read_b128 v[120:123], v86 offset:36864
	s_waitcnt vmcnt(0)
	s_waitcnt vmcnt(0) lgkmcnt(0)
	s_barrier
; #define WAIT_V0() asm volatile("s_waitcnt vmcnt(0)" ::: "memory")
; DI void gemm_core(char* smem, int nk, const char* Ab, const char* Bb, const unsigned (&aoff)[4], const unsigned (&boff)[4],
;                   f32x16 (&acc)[2][2]) {
;     ...
;   for (int kt = 0; kt < nk; ++kt) {
;     const int cur = kt & 1;
;     if (kt + 1 < nk) stage(cur ^ 1, kt + 1);
;     const char* sb = smem + cur * STAGE_B;
; #pragma unroll
;     for (int ks = 0; ks < 4; ++ks) {
;       bf16x8 af[2], bfr[2];
; #pragma unroll
;       for (int mb = 0; mb < 2; ++mb) af[mb] = *(const bf16x8*)(sb + a_base + mb * 4096 + xo[ks]);
; #pragma unroll
;       for (int nb = 0; nb < 2; ++nb) bfr[nb] = *(const bf16x8*)(sb + b_base + nb * 4096 + xo[ks]);
; #pragma unroll
;       for (int mb = 0; mb < 2; ++mb)
; #pragma unroll
;         for (int nb = 0; nb < 2; ++nb)
;           acc[mb][nb] = __builtin_amdgcn_mfma_f32_32x32x16_bf16(af[mb], bfr[nb], acc[mb][nb], 0, 0, 0);
;     }
;     WAIT_V0();
;     __syncthreads();
;   }
	v_mfma_f32_32x32x16_bf16 v[48:63], v[100:103], v[104:107], v[48:63]
	v_mfma_f32_32x32x16_bf16 v[32:47], v[100:103], v[108:111], v[32:47]
	v_mfma_f32_32x32x16_bf16 v[16:31], v[120:123], v[104:107], v[16:31]
	v_mfma_f32_32x32x16_bf16 v[0:15], v[120:123], v[108:111], v[0:15]
	ds_read_b128 v[100:103], v80
	ds_read_b128 v[104:107], v82 offset:16384
	ds_read_b128 v[108:111], v82 offset:20480
	v_lshl_add_u64 v[116:117], v[64:65], 0, s[38:39]
	global_load_lds_dwordx4 v[116:117], off
	v_lshl_add_u64 v[118:119], v[66:67], 0, s[38:39]
	s_mov_b32 m0, s43
	s_nop 0
	global_load_lds_dwordx4 v[118:119], off
	v_lshl_add_u64 v[116:117], v[68:69], 0, s[38:39]
	s_mov_b32 m0, s44
	s_nop 0
	global_load_lds_dwordx4 v[116:117], off
	v_lshl_add_u64 v[118:119], v[70:71], 0, s[38:39]
	s_mov_b32 m0, s1
	s_nop 0
	global_load_lds_dwordx4 v[118:119], off
	v_lshl_add_u64 v[116:117], v[72:73], 0, s[38:39]
	s_mov_b32 m0, s16
	s_nop 0
	global_load_lds_dwordx4 v[116:117], off
	v_lshl_add_u64 v[118:119], v[74:75], 0, s[38:39]
	s_mov_b32 m0, s17
	s_nop 0
	global_load_lds_dwordx4 v[118:119], off
	v_lshl_add_u64 v[116:117], v[76:77], 0, s[38:39]
	s_mov_b32 m0, s18
	s_nop 0
	global_load_lds_dwordx4 v[116:117], off
	v_lshl_add_u64 v[118:119], v[78:79], 0, s[38:39]
	s_mov_b32 m0, s19
	s_nop 0
	global_load_lds_dwordx4 v[118:119], off
	s_waitcnt lgkmcnt(0)
	v_mfma_f32_32x32x16_bf16 v[48:63], v[100:103], v[104:107], v[48:63]
	s_mov_b32 m0, s20
	v_mfma_f32_32x32x16_bf16 v[32:47], v[100:103], v[108:111], v[32:47]
	ds_read_b128 v[100:103], v80 offset:4096
	s_waitcnt lgkmcnt(0)
	v_mfma_f32_32x32x16_bf16 v[16:31], v[100:103], v[104:107], v[16:31]
	v_mfma_f32_32x32x16_bf16 v[0:15], v[100:103], v[108:111], v[0:15]
	ds_read_b128 v[100:103], v81
	ds_read_b128 v[104:107], v83 offset:16384
	ds_read_b128 v[108:111], v83 offset:20480
	s_waitcnt lgkmcnt(0)
	v_mfma_f32_32x32x16_bf16 v[48:63], v[100:103], v[104:107], v[48:63]
	v_mfma_f32_32x32x16_bf16 v[32:47], v[100:103], v[108:111], v[32:47]
	ds_read_b128 v[100:103], v81 offset:4096
	s_waitcnt lgkmcnt(0)
	v_mfma_f32_32x32x16_bf16 v[16:31], v[100:103], v[104:107], v[16:31]
	v_mfma_f32_32x32x16_bf16 v[0:15], v[100:103], v[108:111], v[0:15]
	ds_read_b128 v[100:103], v84
	ds_read_b128 v[104:107], v85 offset:16384
	ds_read_b128 v[108:111], v85 offset:20480
	s_waitcnt lgkmcnt(0)
	v_mfma_f32_32x32x16_bf16 v[48:63], v[100:103], v[104:107], v[48:63]
	v_mfma_f32_32x32x16_bf16 v[32:47], v[100:103], v[108:111], v[32:47]
	ds_read_b128 v[100:103], v84 offset:4096
	s_waitcnt lgkmcnt(0)
	v_mfma_f32_32x32x16_bf16 v[16:31], v[100:103], v[104:107], v[16:31]
	v_mfma_f32_32x32x16_bf16 v[0:15], v[100:103], v[108:111], v[0:15]
	ds_read_b128 v[100:103], v86
	ds_read_b128 v[104:107], v87 offset:16384
	ds_read_b128 v[108:111], v87 offset:20480
	ds_read_b128 v[120:123], v86 offset:4096
	s_waitcnt vmcnt(0)
	s_waitcnt vmcnt(0) lgkmcnt(0)
	s_barrier
	v_mfma_f32_32x32x16_bf16 v[48:63], v[100:103], v[104:107], v[48:63]
	v_mfma_f32_32x32x16_bf16 v[32:47], v[100:103], v[108:111], v[32:47]
	v_mfma_f32_32x32x16_bf16 v[16:31], v[120:123], v[104:107], v[16:31]
	v_mfma_f32_32x32x16_bf16 v[0:15], v[120:123], v[108:111], v[0:15]
	ds_read_b128 v[100:103], v80 offset:32768
	ds_read_b128 v[104:107], v82 offset:49152
	ds_read_b128 v[108:111], v82 offset:53248
	v_lshl_add_u64 v[116:117], v[64:65], 0, s[30:31]
	global_load_lds_dwordx4 v[116:117], off
	v_lshl_add_u64 v[118:119], v[66:67], 0, s[30:31]
	s_mov_b32 m0, s21
	s_nop 0
	global_load_lds_dwordx4 v[118:119], off
	v_lshl_add_u64 v[116:117], v[68:69], 0, s[30:31]
	s_mov_b32 m0, s22
	s_nop 0
	global_load_lds_dwordx4 v[116:117], off
	v_lshl_add_u64 v[118:119], v[70:71], 0, s[30:31]
	s_mov_b32 m0, s23
	s_nop 0
	global_load_lds_dwordx4 v[118:119], off
	v_lshl_add_u64 v[116:117], v[72:73], 0, s[30:31]
	s_mov_b32 m0, s28
	s_nop 0
	global_load_lds_dwordx4 v[116:117], off
	v_lshl_add_u64 v[118:119], v[74:75], 0, s[30:31]
	s_mov_b32 m0, s29
	s_nop 0
	global_load_lds_dwordx4 v[118:119], off
	v_lshl_add_u64 v[116:117], v[76:77], 0, s[30:31]
	s_mov_b32 m0, s40
	s_nop 0
	global_load_lds_dwordx4 v[116:117], off
	v_lshl_add_u64 v[118:119], v[78:79], 0, s[30:31]
	s_mov_b32 m0, s41
	s_nop 0
	global_load_lds_dwordx4 v[118:119], off
	s_waitcnt lgkmcnt(0)
	v_mfma_f32_32x32x16_bf16 v[48:63], v[100:103], v[104:107], v[48:63]
	s_mov_b32 m0, s42
	v_mfma_f32_32x32x16_bf16 v[32:47], v[100:103], v[108:111], v[32:47]
	ds_read_b128 v[100:103], v80 offset:36864
	s_waitcnt lgkmcnt(0)
	v_mfma_f32_32x32x16_bf16 v[16:31], v[100:103], v[104:107], v[16:31]
	v_mfma_f32_32x32x16_bf16 v[0:15], v[100:103], v[108:111], v[0:15]
	ds_read_b128 v[100:103], v81 offset:32768
	ds_read_b128 v[104:107], v83 offset:49152
	ds_read_b128 v[108:111], v83 offset:53248
	s_waitcnt lgkmcnt(0)
	v_mfma_f32_32x32x16_bf16 v[48:63], v[100:103], v[104:107], v[48:63]
	v_mfma_f32_32x32x16_bf16 v[32:47], v[100:103], v[108:111], v[32:47]
	ds_read_b128 v[100:103], v81 offset:36864
	s_waitcnt lgkmcnt(0)
	v_mfma_f32_32x32x16_bf16 v[16:31], v[100:103], v[104:107], v[16:31]
	v_mfma_f32_32x32x16_bf16 v[0:15], v[100:103], v[108:111], v[0:15]
	ds_read_b128 v[100:103], v84 offset:32768
	ds_read_b128 v[104:107], v85 offset:49152
	ds_read_b128 v[108:111], v85 offset:53248
	s_waitcnt lgkmcnt(0)
	v_mfma_f32_32x32x16_bf16 v[48:63], v[100:103], v[104:107], v[48:63]
	v_mfma_f32_32x32x16_bf16 v[32:47], v[100:103], v[108:111], v[32:47]
	ds_read_b128 v[100:103], v84 offset:36864
	s_waitcnt lgkmcnt(0)
	v_mfma_f32_32x32x16_bf16 v[16:31], v[100:103], v[104:107], v[16:31]
	v_mfma_f32_32x32x16_bf16 v[0:15], v[100:103], v[108:111], v[0:15]
	ds_read_b128 v[100:103], v86 offset:32768
	ds_read_b128 v[104:107], v87 offset:49152
	ds_read_b128 v[108:111], v87 offset:53248
	ds_read_b128 v[120:123], v86 offset:36864
	s_waitcnt vmcnt(0)
	s_waitcnt vmcnt(0) lgkmcnt(0)
	s_barrier
; #define WAIT_V0() asm volatile("s_waitcnt vmcnt(0)" ::: "memory")
; DI void gemm_core(char* smem, int nk, const char* Ab, const char* Bb, const unsigned (&aoff)[4], const unsigned (&boff)[4],
;                   f32x16 (&acc)[2][2]) {
;     ...
;   auto stage = [&](int buf, int kt) __attribute__((always_inline)) {
;     const char* ak = Ab + kt * 128;
;     const char* bk = Bb + kt * 128;
;     char* sa = smem + buf * STAGE_B + w * 4096;
; #pragma unroll
;     for (int i = 0; i < 4; ++i) {
;       __builtin_amdgcn_global_load_lds((const unsigned*)(ak + aoff[i]), (unsigned*)(sa + i * 1024), 16, 0, 0);
;       __builtin_amdgcn_global_load_lds((const unsigned*)(bk + boff[i]), (unsigned*)(sa + 16384 + i * 1024), 16, 0, 0);
;     }
;   };
;   stage(0, 0);
;   WAIT_V0();
;   __syncthreads();
;   for (int kt = 0; kt < nk; ++kt) {
;     const int cur = kt & 1;
;     if (kt + 1 < nk) stage(cur ^ 1, kt + 1);
;     const char* sb = smem + cur * STAGE_B;
; #pragma unroll
;     for (int ks = 0; ks < 4; ++ks) {
;       bf16x8 af[2], bfr[2];
; #pragma unroll
;       for (int mb = 0; mb < 2; ++mb) af[mb] = *(const bf16x8*)(sb + a_base + mb * 4096 + xo[ks]);
; #pragma unroll
;       for (int nb = 0; nb < 2; ++nb) bfr[nb] = *(const bf16x8*)(sb + b_base + nb * 4096 + xo[ks]);
; #pragma unroll
;       for (int mb = 0; mb < 2; ++mb)
; #pragma unroll
;         for (int nb = 0; nb < 2; ++nb)
;           acc[mb][nb] = __builtin_amdgcn_mfma_f32_32x32x16_bf16(af[mb], bfr[nb], acc[mb][nb], 0, 0, 0);
;     }
;     WAIT_V0();
;     __syncthreads();
;   }
	v_mfma_f32_32x32x16_bf16 v[48:63], v[100:103], v[104:107], v[48:63]
	v_mfma_f32_32x32x16_bf16 v[32:47], v[100:103], v[108:111], v[32:47]
	v_mfma_f32_32x32x16_bf16 v[16:31], v[120:123], v[104:107], v[16:31]
	v_mfma_f32_32x32x16_bf16 v[0:15], v[120:123], v[108:111], v[0:15]
	ds_read_b128 v[100:103], v80
	ds_read_b128 v[104:107], v82 offset:16384
	ds_read_b128 v[108:111], v82 offset:20480
	v_lshl_add_u64 v[116:117], v[64:65], 0, s[46:47]
	global_load_lds_dwordx4 v[116:117], off
	v_lshl_add_u64 v[118:119], v[66:67], 0, s[46:47]
	s_mov_b32 m0, s43
	s_nop 0
	global_load_lds_dwordx4 v[118:119], off
	v_lshl_add_u64 v[116:117], v[68:69], 0, s[46:47]
	s_mov_b32 m0, s44
	s_nop 0
	global_load_lds_dwordx4 v[116:117], off
	v_lshl_add_u64 v[118:119], v[70:71], 0, s[46:47]
	s_mov_b32 m0, s1
	s_nop 0
	global_load_lds_dwordx4 v[118:119], off
	v_lshl_add_u64 v[116:117], v[72:73], 0, s[46:47]
	s_mov_b32 m0, s16
	s_nop 0
	global_load_lds_dwordx4 v[116:117], off
	v_lshl_add_u64 v[118:119], v[74:75], 0, s[46:47]
	s_mov_b32 m0, s17
	s_nop 0
	global_load_lds_dwordx4 v[118:119], off
	v_lshl_add_u64 v[116:117], v[76:77], 0, s[46:47]
	s_mov_b32 m0, s18
	s_nop 0
	global_load_lds_dwordx4 v[116:117], off
	v_lshl_add_u64 v[118:119], v[78:79], 0, s[46:47]
	s_mov_b32 m0, s19
	s_nop 0
	global_load_lds_dwordx4 v[118:119], off
	s_waitcnt lgkmcnt(0)
	v_mfma_f32_32x32x16_bf16 v[48:63], v[100:103], v[104:107], v[48:63]
	s_mov_b32 m0, s20
	v_mfma_f32_32x32x16_bf16 v[32:47], v[100:103], v[108:111], v[32:47]
	ds_read_b128 v[100:103], v80 offset:4096
	s_waitcnt lgkmcnt(0)
	v_mfma_f32_32x32x16_bf16 v[16:31], v[100:103], v[104:107], v[16:31]
	v_mfma_f32_32x32x16_bf16 v[0:15], v[100:103], v[108:111], v[0:15]
	ds_read_b128 v[100:103], v81
	ds_read_b128 v[104:107], v83 offset:16384
	ds_read_b128 v[108:111], v83 offset:20480
	s_waitcnt lgkmcnt(0)
	v_mfma_f32_32x32x16_bf16 v[48:63], v[100:103], v[104:107], v[48:63]
	v_mfma_f32_32x32x16_bf16 v[32:47], v[100:103], v[108:111], v[32:47]
	ds_read_b128 v[100:103], v81 offset:4096
	s_waitcnt lgkmcnt(0)
	v_mfma_f32_32x32x16_bf16 v[16:31], v[100:103], v[104:107], v[16:31]
	v_mfma_f32_32x32x16_bf16 v[0:15], v[100:103], v[108:111], v[0:15]
	ds_read_b128 v[100:103], v84
	ds_read_b128 v[104:107], v85 offset:16384
	ds_read_b128 v[108:111], v85 offset:20480
	s_waitcnt lgkmcnt(0)
	v_mfma_f32_32x32x16_bf16 v[48:63], v[100:103], v[104:107], v[48:63]
	v_mfma_f32_32x32x16_bf16 v[32:47], v[100:103], v[108:111], v[32:47]
	ds_read_b128 v[100:103], v84 offset:4096
	s_waitcnt lgkmcnt(0)
	v_mfma_f32_32x32x16_bf16 v[16:31], v[100:103], v[104:107], v[16:31]
	v_mfma_f32_32x32x16_bf16 v[0:15], v[100:103], v[108:111], v[0:15]
	ds_read_b128 v[100:103], v86
	ds_read_b128 v[104:107], v87 offset:16384
	ds_read_b128 v[108:111], v87 offset:20480
	ds_read_b128 v[120:123], v86 offset:4096
	s_waitcnt vmcnt(0)
	s_waitcnt vmcnt(0) lgkmcnt(0)
	s_barrier
	v_mfma_f32_32x32x16_bf16 v[48:63], v[100:103], v[104:107], v[48:63]
	v_mfma_f32_32x32x16_bf16 v[32:47], v[100:103], v[108:111], v[32:47]
	v_mfma_f32_32x32x16_bf16 v[16:31], v[120:123], v[104:107], v[16:31]
	v_mfma_f32_32x32x16_bf16 v[0:15], v[120:123], v[108:111], v[0:15]
	ds_read_b128 v[100:103], v80 offset:32768
	ds_read_b128 v[104:107], v82 offset:49152
	ds_read_b128 v[108:111], v82 offset:53248
	v_lshl_add_u64 v[116:117], v[64:65], 0, s[48:49]
	global_load_lds_dwordx4 v[116:117], off
	v_lshl_add_u64 v[118:119], v[66:67], 0, s[48:49]
	s_mov_b32 m0, s21
	s_nop 0
	global_load_lds_dwordx4 v[118:119], off
	v_lshl_add_u64 v[116:117], v[68:69], 0, s[48:49]
	s_mov_b32 m0, s22
	s_nop 0
	global_load_lds_dwordx4 v[116:117], off
	v_lshl_add_u64 v[118:119], v[70:71], 0, s[48:49]
	s_mov_b32 m0, s23
	s_nop 0
	global_load_lds_dwordx4 v[118:119], off
	v_lshl_add_u64 v[116:117], v[72:73], 0, s[48:49]
	s_mov_b32 m0, s28
	s_nop 0
	global_load_lds_dwordx4 v[116:117], off
	v_lshl_add_u64 v[118:119], v[74:75], 0, s[48:49]
	s_mov_b32 m0, s29
	s_nop 0
	global_load_lds_dwordx4 v[118:119], off
	v_lshl_add_u64 v[116:117], v[76:77], 0, s[48:49]
	s_mov_b32 m0, s40
	s_nop 0
	global_load_lds_dwordx4 v[116:117], off
	v_lshl_add_u64 v[118:119], v[78:79], 0, s[48:49]
	s_mov_b32 m0, s41
	s_nop 0
	global_load_lds_dwordx4 v[118:119], off
	s_waitcnt lgkmcnt(0)
	v_mfma_f32_32x32x16_bf16 v[48:63], v[100:103], v[104:107], v[48:63]
	s_mov_b32 m0, s42
	v_readfirstlane_b32 s42, v93
	v_mfma_f32_32x32x16_bf16 v[32:47], v[100:103], v[108:111], v[32:47]
	ds_read_b128 v[100:103], v80 offset:36864
	s_waitcnt lgkmcnt(0)
	v_mfma_f32_32x32x16_bf16 v[16:31], v[100:103], v[104:107], v[16:31]
	v_mfma_f32_32x32x16_bf16 v[0:15], v[100:103], v[108:111], v[0:15]
	ds_read_b128 v[100:103], v81 offset:32768
	ds_read_b128 v[104:107], v83 offset:49152
	ds_read_b128 v[108:111], v83 offset:53248
	s_waitcnt lgkmcnt(0)
	v_mfma_f32_32x32x16_bf16 v[48:63], v[100:103], v[104:107], v[48:63]
	v_mfma_f32_32x32x16_bf16 v[32:47], v[100:103], v[108:111], v[32:47]
	ds_read_b128 v[100:103], v81 offset:36864
	s_waitcnt lgkmcnt(0)
	v_mfma_f32_32x32x16_bf16 v[16:31], v[100:103], v[104:107], v[16:31]
	v_mfma_f32_32x32x16_bf16 v[0:15], v[100:103], v[108:111], v[0:15]
	ds_read_b128 v[100:103], v84 offset:32768
	ds_read_b128 v[104:107], v85 offset:49152
	ds_read_b128 v[108:111], v85 offset:53248
	s_waitcnt lgkmcnt(0)
	v_mfma_f32_32x32x16_bf16 v[48:63], v[100:103], v[104:107], v[48:63]
	v_mfma_f32_32x32x16_bf16 v[32:47], v[100:103], v[108:111], v[32:47]
	ds_read_b128 v[100:103], v84 offset:36864
	s_waitcnt lgkmcnt(0)
	v_mfma_f32_32x32x16_bf16 v[16:31], v[100:103], v[104:107], v[16:31]
	v_mfma_f32_32x32x16_bf16 v[0:15], v[100:103], v[108:111], v[0:15]
	ds_read_b128 v[100:103], v86 offset:32768
	ds_read_b128 v[104:107], v87 offset:49152
	ds_read_b128 v[108:111], v87 offset:53248
	ds_read_b128 v[120:123], v86 offset:36864
	s_waitcnt vmcnt(0)
	s_waitcnt vmcnt(0) lgkmcnt(0)
	s_barrier
; #define WAIT_V0() asm volatile("s_waitcnt vmcnt(0)" ::: "memory")
; DI void gemm_core(char* smem, int nk, const char* Ab, const char* Bb, const unsigned (&aoff)[4], const unsigned (&boff)[4],
;                   f32x16 (&acc)[2][2]) {
;     ...
;   auto stage = [&](int buf, int kt) __attribute__((always_inline)) {
;     const char* ak = Ab + kt * 128;
;     const char* bk = Bb + kt * 128;
;     char* sa = smem + buf * STAGE_B + w * 4096;
; #pragma unroll
;     for (int i = 0; i < 4; ++i) {
;       __builtin_amdgcn_global_load_lds((const unsigned*)(ak + aoff[i]), (unsigned*)(sa + i * 1024), 16, 0, 0);
;       __builtin_amdgcn_global_load_lds((const unsigned*)(bk + boff[i]), (unsigned*)(sa + 16384 + i * 1024), 16, 0, 0);
;     }
;   };
;   stage(0, 0);
;   WAIT_V0();
;   __syncthreads();
;   for (int kt = 0; kt < nk; ++kt) {
;     const int cur = kt & 1;
;     if (kt + 1 < nk) stage(cur ^ 1, kt + 1);
;     const char* sb = smem + cur * STAGE_B;
; #pragma unroll
;     for (int ks = 0; ks < 4; ++ks) {
;       bf16x8 af[2], bfr[2];
; #pragma unroll
;       for (int mb = 0; mb < 2; ++mb) af[mb] = *(const bf16x8*)(sb + a_base + mb * 4096 + xo[ks]);
; #pragma unroll
;       for (int nb = 0; nb < 2; ++nb) bfr[nb] = *(const bf16x8*)(sb + b_base + nb * 4096 + xo[ks]);
; #pragma unroll
;       for (int mb = 0; mb < 2; ++mb)
; #pragma unroll
;         for (int nb = 0; nb < 2; ++nb)
;           acc[mb][nb] = __builtin_amdgcn_mfma_f32_32x32x16_bf16(af[mb], bfr[nb], acc[mb][nb], 0, 0, 0);
;     }
;     WAIT_V0();
;     __syncthreads();
;   }
	v_mfma_f32_32x32x16_bf16 v[48:63], v[100:103], v[104:107], v[48:63]
	v_mfma_f32_32x32x16_bf16 v[32:47], v[100:103], v[108:111], v[32:47]
	v_mfma_f32_32x32x16_bf16 v[16:31], v[120:123], v[104:107], v[16:31]
	v_mfma_f32_32x32x16_bf16 v[0:15], v[120:123], v[108:111], v[0:15]
	ds_read_b128 v[100:103], v80
	ds_read_b128 v[104:107], v82 offset:16384
	ds_read_b128 v[108:111], v82 offset:20480
	v_lshl_add_u64 v[116:117], v[64:65], 0, s[50:51]
	global_load_lds_dwordx4 v[116:117], off
	v_lshl_add_u64 v[118:119], v[66:67], 0, s[50:51]
	s_mov_b32 m0, s43
	v_readfirstlane_b32 s43, v94
	global_load_lds_dwordx4 v[118:119], off
	v_lshl_add_u64 v[116:117], v[68:69], 0, s[50:51]
	s_mov_b32 m0, s44
	v_readfirstlane_b32 s44, v95
	global_load_lds_dwordx4 v[116:117], off
	v_lshl_add_u64 v[118:119], v[70:71], 0, s[50:51]
	s_mov_b32 m0, s1
	s_nop 0
	global_load_lds_dwordx4 v[118:119], off
	v_lshl_add_u64 v[116:117], v[72:73], 0, s[50:51]
	s_mov_b32 m0, s16
	s_nop 0
	global_load_lds_dwordx4 v[116:117], off
	v_lshl_add_u64 v[118:119], v[74:75], 0, s[50:51]
	s_mov_b32 m0, s17
	s_nop 0
	global_load_lds_dwordx4 v[118:119], off
	v_lshl_add_u64 v[116:117], v[76:77], 0, s[50:51]
	s_mov_b32 m0, s18
	s_nop 0
	global_load_lds_dwordx4 v[116:117], off
	v_lshl_add_u64 v[118:119], v[78:79], 0, s[50:51]
	s_mov_b32 m0, s19
	s_nop 0
	global_load_lds_dwordx4 v[118:119], off
	s_waitcnt lgkmcnt(0)
	v_mfma_f32_32x32x16_bf16 v[48:63], v[100:103], v[104:107], v[48:63]
	s_mov_b32 m0, s20
	v_readfirstlane_b32 s20, v97
	v_mfma_f32_32x32x16_bf16 v[32:47], v[100:103], v[108:111], v[32:47]
	ds_read_b128 v[100:103], v80 offset:4096
	s_waitcnt lgkmcnt(0)
	v_mfma_f32_32x32x16_bf16 v[16:31], v[100:103], v[104:107], v[16:31]
	v_mfma_f32_32x32x16_bf16 v[0:15], v[100:103], v[108:111], v[0:15]
	ds_read_b128 v[100:103], v81
	ds_read_b128 v[104:107], v83 offset:16384
	ds_read_b128 v[108:111], v83 offset:20480
	s_waitcnt lgkmcnt(0)
	v_mfma_f32_32x32x16_bf16 v[48:63], v[100:103], v[104:107], v[48:63]
	v_mfma_f32_32x32x16_bf16 v[32:47], v[100:103], v[108:111], v[32:47]
	ds_read_b128 v[100:103], v81 offset:4096
	s_waitcnt lgkmcnt(0)
	v_mfma_f32_32x32x16_bf16 v[16:31], v[100:103], v[104:107], v[16:31]
	v_mfma_f32_32x32x16_bf16 v[0:15], v[100:103], v[108:111], v[0:15]
	ds_read_b128 v[100:103], v84
	ds_read_b128 v[104:107], v85 offset:16384
	ds_read_b128 v[108:111], v85 offset:20480
	s_waitcnt lgkmcnt(0)
	v_mfma_f32_32x32x16_bf16 v[48:63], v[100:103], v[104:107], v[48:63]
	v_mfma_f32_32x32x16_bf16 v[32:47], v[100:103], v[108:111], v[32:47]
	ds_read_b128 v[100:103], v84 offset:4096
	s_waitcnt lgkmcnt(0)
	v_mfma_f32_32x32x16_bf16 v[16:31], v[100:103], v[104:107], v[16:31]
	v_mfma_f32_32x32x16_bf16 v[0:15], v[100:103], v[108:111], v[0:15]
	ds_read_b128 v[100:103], v86
	ds_read_b128 v[104:107], v87 offset:16384
	ds_read_b128 v[108:111], v87 offset:20480
	ds_read_b128 v[120:123], v86 offset:4096
	s_waitcnt vmcnt(0)
	s_waitcnt vmcnt(0) lgkmcnt(0)
	s_barrier
	v_mfma_f32_32x32x16_bf16 v[48:63], v[100:103], v[104:107], v[48:63]
	v_mfma_f32_32x32x16_bf16 v[32:47], v[100:103], v[108:111], v[32:47]
	v_mfma_f32_32x32x16_bf16 v[16:31], v[120:123], v[104:107], v[16:31]
	v_mfma_f32_32x32x16_bf16 v[0:15], v[120:123], v[108:111], v[0:15]
	v_lshl_add_u64 v[100:101], v[64:65], 0, s[52:53]
	global_load_lds_dwordx4 v[100:101], off
	v_lshl_add_u64 v[100:101], v[66:67], 0, s[52:53]
	s_mov_b32 m0, s21
	v_readfirstlane_b32 s21, v96
	global_load_lds_dwordx4 v[100:101], off
	v_lshl_add_u64 v[100:101], v[68:69], 0, s[52:53]
	s_mov_b32 m0, s22
	v_readfirstlane_b32 s22, v98
	global_load_lds_dwordx4 v[100:101], off
	v_lshl_add_u64 v[100:101], v[70:71], 0, s[52:53]
	s_mov_b32 m0, s23
	v_lshl_add_u64 v[96:97], v[68:69], 0, s[54:55]
	global_load_lds_dwordx4 v[100:101], off
	v_lshl_add_u64 v[100:101], v[72:73], 0, s[52:53]
	s_mov_b32 m0, s28
	v_readfirstlane_b32 s23, v89
	global_load_lds_dwordx4 v[100:101], off
	v_lshl_add_u64 v[100:101], v[74:75], 0, s[52:53]
	s_mov_b32 m0, s29
	v_readfirstlane_b32 s28, v88
	global_load_lds_dwordx4 v[100:101], off
	v_lshl_add_u64 v[100:101], v[76:77], 0, s[52:53]
	s_mov_b32 m0, s40
	v_readfirstlane_b32 s29, v90
	global_load_lds_dwordx4 v[100:101], off
	v_lshl_add_u64 v[100:101], v[78:79], 0, s[52:53]
	s_mov_b32 m0, s41
	v_lshl_add_u64 v[88:89], v[68:69], 0, s[56:57]
	global_load_lds_dwordx4 v[100:101], off
	ds_read_b128 v[100:103], v80 offset:32768
	ds_read_b128 v[104:107], v82 offset:49152
	ds_read_b128 v[108:111], v82 offset:53248
	s_waitcnt lgkmcnt(0)
	v_mfma_f32_32x32x16_bf16 v[48:63], v[100:103], v[104:107], v[48:63]
	s_mov_b32 m0, s20
	v_readfirstlane_b32 s40, v91
	v_readfirstlane_b32 s41, v92
	v_mfma_f32_32x32x16_bf16 v[32:47], v[100:103], v[108:111], v[32:47]
	ds_read_b128 v[100:103], v80 offset:36864
	s_waitcnt lgkmcnt(0)
	v_mfma_f32_32x32x16_bf16 v[16:31], v[100:103], v[104:107], v[16:31]
	v_mfma_f32_32x32x16_bf16 v[0:15], v[100:103], v[108:111], v[0:15]
	ds_read_b128 v[100:103], v81 offset:32768
	ds_read_b128 v[104:107], v83 offset:49152
	ds_read_b128 v[108:111], v83 offset:53248
	s_waitcnt lgkmcnt(0)
	v_mfma_f32_32x32x16_bf16 v[48:63], v[100:103], v[104:107], v[48:63]
	v_mfma_f32_32x32x16_bf16 v[32:47], v[100:103], v[108:111], v[32:47]
	ds_read_b128 v[100:103], v81 offset:36864
	s_waitcnt lgkmcnt(0)
	v_mfma_f32_32x32x16_bf16 v[16:31], v[100:103], v[104:107], v[16:31]
	v_mfma_f32_32x32x16_bf16 v[0:15], v[100:103], v[108:111], v[0:15]
	ds_read_b128 v[100:103], v84 offset:32768
	ds_read_b128 v[104:107], v85 offset:49152
	ds_read_b128 v[108:111], v85 offset:53248
	s_waitcnt lgkmcnt(0)
	v_mfma_f32_32x32x16_bf16 v[48:63], v[100:103], v[104:107], v[48:63]
	v_mfma_f32_32x32x16_bf16 v[32:47], v[100:103], v[108:111], v[32:47]
	ds_read_b128 v[100:103], v84 offset:36864
	s_waitcnt lgkmcnt(0)
	v_mfma_f32_32x32x16_bf16 v[16:31], v[100:103], v[104:107], v[16:31]
	v_mfma_f32_32x32x16_bf16 v[0:15], v[100:103], v[108:111], v[0:15]
	ds_read_b128 v[100:103], v86 offset:32768
	ds_read_b128 v[104:107], v87 offset:49152
	ds_read_b128 v[108:111], v87 offset:53248
	ds_read_b128 v[120:123], v86 offset:36864
	s_waitcnt vmcnt(0)
	s_waitcnt vmcnt(0) lgkmcnt(0)
	s_barrier
; #define WAIT_V0() asm volatile("s_waitcnt vmcnt(0)" ::: "memory")
; DI void gemm_core(char* smem, int nk, const char* Ab, const char* Bb, const unsigned (&aoff)[4], const unsigned (&boff)[4],
;                   f32x16 (&acc)[2][2]) {
;     ...
;   auto stage = [&](int buf, int kt) __attribute__((always_inline)) {
;     const char* ak = Ab + kt * 128;
;     const char* bk = Bb + kt * 128;
;     char* sa = smem + buf * STAGE_B + w * 4096;
; #pragma unroll
;     for (int i = 0; i < 4; ++i) {
;       __builtin_amdgcn_global_load_lds((const unsigned*)(ak + aoff[i]), (unsigned*)(sa + i * 1024), 16, 0, 0);
;       __builtin_amdgcn_global_load_lds((const unsigned*)(bk + boff[i]), (unsigned*)(sa + 16384 + i * 1024), 16, 0, 0);
;     }
;   };
;   stage(0, 0);
;   WAIT_V0();
;   __syncthreads();
;   for (int kt = 0; kt < nk; ++kt) {
;     const int cur = kt & 1;
;     if (kt + 1 < nk) stage(cur ^ 1, kt + 1);
;     const char* sb = smem + cur * STAGE_B;
; #pragma unroll
;     for (int ks = 0; ks < 4; ++ks) {
;       bf16x8 af[2], bfr[2];
; #pragma unroll
;       for (int mb = 0; mb < 2; ++mb) af[mb] = *(const bf16x8*)(sb + a_base + mb * 4096 + xo[ks]);
; #pragma unroll
;       for (int nb = 0; nb < 2; ++nb) bfr[nb] = *(const bf16x8*)(sb + b_base + nb * 4096 + xo[ks]);
; #pragma unroll
;       for (int mb = 0; mb < 2; ++mb)
; #pragma unroll
;         for (int nb = 0; nb < 2; ++nb)
;           acc[mb][nb] = __builtin_amdgcn_mfma_f32_32x32x16_bf16(af[mb], bfr[nb], acc[mb][nb], 0, 0, 0);
;     }
;     WAIT_V0();
;     __syncthreads();
;   }
	v_mfma_f32_32x32x16_bf16 v[48:63], v[100:103], v[104:107], v[48:63]
	v_mfma_f32_32x32x16_bf16 v[32:47], v[100:103], v[108:111], v[32:47]
	v_mfma_f32_32x32x16_bf16 v[16:31], v[120:123], v[104:107], v[16:31]
	v_mfma_f32_32x32x16_bf16 v[0:15], v[120:123], v[108:111], v[0:15]
	v_lshl_add_u64 v[100:101], v[64:65], 0, s[54:55]
	global_load_lds_dwordx4 v[100:101], off
	v_lshl_add_u64 v[100:101], v[66:67], 0, s[54:55]
	s_mov_b32 m0, s21
	s_nop 0
	global_load_lds_dwordx4 v[100:101], off
	s_mov_b32 m0, s22
	s_nop 0
	global_load_lds_dwordx4 v[96:97], off
	v_lshl_add_u64 v[96:97], v[70:71], 0, s[54:55]
	s_mov_b32 m0, s1
	s_nop 0
	global_load_lds_dwordx4 v[96:97], off
	v_lshl_add_u64 v[96:97], v[72:73], 0, s[54:55]
	s_mov_b32 m0, s16
	s_nop 0
	global_load_lds_dwordx4 v[96:97], off
	v_lshl_add_u64 v[96:97], v[74:75], 0, s[54:55]
	s_mov_b32 m0, s17
	s_nop 0
	global_load_lds_dwordx4 v[96:97], off
	v_lshl_add_u64 v[96:97], v[76:77], 0, s[54:55]
	s_mov_b32 m0, s18
	s_nop 0
	global_load_lds_dwordx4 v[96:97], off
	v_lshl_add_u64 v[96:97], v[78:79], 0, s[54:55]
	s_mov_b32 m0, s19
	s_nop 0
	global_load_lds_dwordx4 v[96:97], off
	ds_read_b128 v[96:99], v80
	ds_read_b128 v[100:103], v82 offset:16384
	ds_read_b128 v[104:107], v82 offset:20480
	s_waitcnt lgkmcnt(0)
	v_mfma_f32_32x32x16_bf16 v[48:63], v[96:99], v[100:103], v[48:63]
	s_mov_b32 m0, s23
	v_mfma_f32_32x32x16_bf16 v[32:47], v[96:99], v[104:107], v[32:47]
	ds_read_b128 v[96:99], v80 offset:4096
	s_waitcnt lgkmcnt(0)
	v_mfma_f32_32x32x16_bf16 v[16:31], v[96:99], v[100:103], v[16:31]
	v_mfma_f32_32x32x16_bf16 v[0:15], v[96:99], v[104:107], v[0:15]
	ds_read_b128 v[96:99], v81
	ds_read_b128 v[100:103], v83 offset:16384
	ds_read_b128 v[104:107], v83 offset:20480
	s_waitcnt lgkmcnt(0)
	v_mfma_f32_32x32x16_bf16 v[48:63], v[96:99], v[100:103], v[48:63]
	v_mfma_f32_32x32x16_bf16 v[32:47], v[96:99], v[104:107], v[32:47]
	ds_read_b128 v[96:99], v81 offset:4096
	s_waitcnt lgkmcnt(0)
	v_mfma_f32_32x32x16_bf16 v[16:31], v[96:99], v[100:103], v[16:31]
	v_mfma_f32_32x32x16_bf16 v[0:15], v[96:99], v[104:107], v[0:15]
	ds_read_b128 v[96:99], v84
	ds_read_b128 v[100:103], v85 offset:16384
	ds_read_b128 v[104:107], v85 offset:20480
	s_waitcnt lgkmcnt(0)
	v_mfma_f32_32x32x16_bf16 v[48:63], v[96:99], v[100:103], v[48:63]
	v_mfma_f32_32x32x16_bf16 v[32:47], v[96:99], v[104:107], v[32:47]
	ds_read_b128 v[96:99], v84 offset:4096
	s_waitcnt lgkmcnt(0)
	v_mfma_f32_32x32x16_bf16 v[16:31], v[96:99], v[100:103], v[16:31]
	v_mfma_f32_32x32x16_bf16 v[0:15], v[96:99], v[104:107], v[0:15]
	ds_read_b128 v[96:99], v86
	ds_read_b128 v[100:103], v87 offset:16384
	ds_read_b128 v[104:107], v87 offset:20480
	ds_read_b128 v[120:123], v86 offset:4096
	s_waitcnt vmcnt(0)
	s_waitcnt vmcnt(0) lgkmcnt(0)
	s_barrier
	v_mfma_f32_32x32x16_bf16 v[48:63], v[96:99], v[100:103], v[48:63]
	v_mfma_f32_32x32x16_bf16 v[32:47], v[96:99], v[104:107], v[32:47]
	v_mfma_f32_32x32x16_bf16 v[16:31], v[120:123], v[100:103], v[16:31]
	v_mfma_f32_32x32x16_bf16 v[0:15], v[120:123], v[104:107], v[0:15]
	v_lshl_add_u64 v[96:97], v[64:65], 0, s[56:57]
	global_load_lds_dwordx4 v[96:97], off
	v_lshl_add_u64 v[96:97], v[66:67], 0, s[56:57]
	s_mov_b32 m0, s28
	s_nop 0
	global_load_lds_dwordx4 v[96:97], off
	s_mov_b32 m0, s29
	s_nop 0
	global_load_lds_dwordx4 v[88:89], off
	v_lshl_add_u64 v[88:89], v[70:71], 0, s[56:57]
	s_mov_b32 m0, s40
	s_nop 0
	global_load_lds_dwordx4 v[88:89], off
	v_lshl_add_u64 v[88:89], v[72:73], 0, s[56:57]
	s_mov_b32 m0, s41
	s_nop 0
	global_load_lds_dwordx4 v[88:89], off
	v_lshl_add_u64 v[88:89], v[74:75], 0, s[56:57]
	s_mov_b32 m0, s42
	s_nop 0
	global_load_lds_dwordx4 v[88:89], off
	v_lshl_add_u64 v[88:89], v[76:77], 0, s[56:57]
	s_mov_b32 m0, s43
	s_nop 0
	global_load_lds_dwordx4 v[88:89], off
	v_lshl_add_u64 v[88:89], v[78:79], 0, s[56:57]
	s_mov_b32 m0, s44
	s_nop 0
	global_load_lds_dwordx4 v[88:89], off
	ds_read_b128 v[88:91], v80 offset:32768
	ds_read_b128 v[92:95], v82 offset:49152
	ds_read_b128 v[96:99], v82 offset:53248
	s_waitcnt lgkmcnt(0)
	v_mfma_f32_32x32x16_bf16 v[48:63], v[88:91], v[92:95], v[48:63]
	s_mov_b32 m0, s20
	v_mfma_f32_32x32x16_bf16 v[32:47], v[88:91], v[96:99], v[32:47]
	ds_read_b128 v[88:91], v80 offset:36864
	s_waitcnt lgkmcnt(0)
	v_mfma_f32_32x32x16_bf16 v[16:31], v[88:91], v[92:95], v[16:31]
	v_mfma_f32_32x32x16_bf16 v[0:15], v[88:91], v[96:99], v[0:15]
	ds_read_b128 v[88:91], v81 offset:32768
	ds_read_b128 v[92:95], v83 offset:49152
	ds_read_b128 v[96:99], v83 offset:53248
	s_waitcnt lgkmcnt(0)
	v_mfma_f32_32x32x16_bf16 v[48:63], v[88:91], v[92:95], v[48:63]
	v_mfma_f32_32x32x16_bf16 v[32:47], v[88:91], v[96:99], v[32:47]
	ds_read_b128 v[88:91], v81 offset:36864
	s_waitcnt lgkmcnt(0)
	v_mfma_f32_32x32x16_bf16 v[16:31], v[88:91], v[92:95], v[16:31]
	v_mfma_f32_32x32x16_bf16 v[0:15], v[88:91], v[96:99], v[0:15]
	ds_read_b128 v[88:91], v84 offset:32768
	ds_read_b128 v[92:95], v85 offset:49152
	ds_read_b128 v[96:99], v85 offset:53248
	s_waitcnt lgkmcnt(0)
	v_mfma_f32_32x32x16_bf16 v[48:63], v[88:91], v[92:95], v[48:63]
	v_mfma_f32_32x32x16_bf16 v[32:47], v[88:91], v[96:99], v[32:47]
	ds_read_b128 v[88:91], v84 offset:36864
	s_waitcnt lgkmcnt(0)
	v_mfma_f32_32x32x16_bf16 v[16:31], v[88:91], v[92:95], v[16:31]
	v_mfma_f32_32x32x16_bf16 v[0:15], v[88:91], v[96:99], v[0:15]
	ds_read_b128 v[88:91], v86 offset:32768
	ds_read_b128 v[92:95], v87 offset:49152
	ds_read_b128 v[96:99], v87 offset:53248
	ds_read_b128 v[120:123], v86 offset:36864
	s_waitcnt vmcnt(0)
	s_waitcnt vmcnt(0) lgkmcnt(0)
	s_barrier
; #define WAIT_V0() asm volatile("s_waitcnt vmcnt(0)" ::: "memory")
; DI void gemm_core(char* smem, int nk, const char* Ab, const char* Bb, const unsigned (&aoff)[4], const unsigned (&boff)[4],
;                   f32x16 (&acc)[2][2]) {
;     ...
;   auto stage = [&](int buf, int kt) __attribute__((always_inline)) {
;     const char* ak = Ab + kt * 128;
;     const char* bk = Bb + kt * 128;
;     char* sa = smem + buf * STAGE_B + w * 4096;
; #pragma unroll
;     for (int i = 0; i < 4; ++i) {
;       __builtin_amdgcn_global_load_lds((const unsigned*)(ak + aoff[i]), (unsigned*)(sa + i * 1024), 16, 0, 0);
;       __builtin_amdgcn_global_load_lds((const unsigned*)(bk + boff[i]), (unsigned*)(sa + 16384 + i * 1024), 16, 0, 0);
;     }
;   };
;   stage(0, 0);
;   WAIT_V0();
;   __syncthreads();
;   for (int kt = 0; kt < nk; ++kt) {
;     const int cur = kt & 1;
;     if (kt + 1 < nk) stage(cur ^ 1, kt + 1);
;     const char* sb = smem + cur * STAGE_B;
; #pragma unroll
;     for (int ks = 0; ks < 4; ++ks) {
;       bf16x8 af[2], bfr[2];
; #pragma unroll
;       for (int mb = 0; mb < 2; ++mb) af[mb] = *(const bf16x8*)(sb + a_base + mb * 4096 + xo[ks]);
; #pragma unroll
;       for (int nb = 0; nb < 2; ++nb) bfr[nb] = *(const bf16x8*)(sb + b_base + nb * 4096 + xo[ks]);
; #pragma unroll
;       for (int mb = 0; mb < 2; ++mb)
; #pragma unroll
;         for (int nb = 0; nb < 2; ++nb)
;           acc[mb][nb] = __builtin_amdgcn_mfma_f32_32x32x16_bf16(af[mb], bfr[nb], acc[mb][nb], 0, 0, 0);
;     }
;     WAIT_V0();
;     __syncthreads();
;   }
	v_mfma_f32_32x32x16_bf16 v[48:63], v[88:91], v[92:95], v[48:63]
	v_mfma_f32_32x32x16_bf16 v[32:47], v[88:91], v[96:99], v[32:47]
	v_mfma_f32_32x32x16_bf16 v[16:31], v[120:123], v[92:95], v[16:31]
	v_mfma_f32_32x32x16_bf16 v[0:15], v[120:123], v[96:99], v[0:15]
	ds_read_b128 v[88:91], v80
	ds_read_b128 v[92:95], v82 offset:16384
	ds_read_b128 v[96:99], v82 offset:20480
	v_lshl_add_u64 v[116:117], v[64:65], 0, s[58:59]
	global_load_lds_dwordx4 v[116:117], off
	v_lshl_add_u64 v[118:119], v[66:67], 0, s[58:59]
	s_mov_b32 m0, s21
	s_nop 0
	global_load_lds_dwordx4 v[118:119], off
	v_lshl_add_u64 v[116:117], v[68:69], 0, s[58:59]
	s_mov_b32 m0, s22
	s_nop 0
	global_load_lds_dwordx4 v[116:117], off
	v_lshl_add_u64 v[118:119], v[70:71], 0, s[58:59]
	s_mov_b32 m0, s1
	s_nop 0
	global_load_lds_dwordx4 v[118:119], off
	v_lshl_add_u64 v[116:117], v[72:73], 0, s[58:59]
	s_mov_b32 m0, s16
	s_nop 0
	global_load_lds_dwordx4 v[116:117], off
	v_lshl_add_u64 v[118:119], v[74:75], 0, s[58:59]
	s_mov_b32 m0, s17
	s_nop 0
	global_load_lds_dwordx4 v[118:119], off
	v_lshl_add_u64 v[116:117], v[76:77], 0, s[58:59]
	s_mov_b32 m0, s18
	s_nop 0
	global_load_lds_dwordx4 v[116:117], off
	v_lshl_add_u64 v[118:119], v[78:79], 0, s[58:59]
	s_mov_b32 m0, s19
	s_nop 0
	global_load_lds_dwordx4 v[118:119], off
	s_waitcnt lgkmcnt(0)
	v_mfma_f32_32x32x16_bf16 v[48:63], v[88:91], v[92:95], v[48:63]
	s_mov_b32 m0, s23
	v_mfma_f32_32x32x16_bf16 v[32:47], v[88:91], v[96:99], v[32:47]
	ds_read_b128 v[88:91], v80 offset:4096
	s_waitcnt lgkmcnt(0)
	v_mfma_f32_32x32x16_bf16 v[16:31], v[88:91], v[92:95], v[16:31]
	v_mfma_f32_32x32x16_bf16 v[0:15], v[88:91], v[96:99], v[0:15]
	ds_read_b128 v[88:91], v81
	ds_read_b128 v[92:95], v83 offset:16384
	ds_read_b128 v[96:99], v83 offset:20480
	s_waitcnt lgkmcnt(0)
	v_mfma_f32_32x32x16_bf16 v[48:63], v[88:91], v[92:95], v[48:63]
	v_mfma_f32_32x32x16_bf16 v[32:47], v[88:91], v[96:99], v[32:47]
	ds_read_b128 v[88:91], v81 offset:4096
	s_waitcnt lgkmcnt(0)
	v_mfma_f32_32x32x16_bf16 v[16:31], v[88:91], v[92:95], v[16:31]
	v_mfma_f32_32x32x16_bf16 v[0:15], v[88:91], v[96:99], v[0:15]
	ds_read_b128 v[88:91], v84
	ds_read_b128 v[92:95], v85 offset:16384
	ds_read_b128 v[96:99], v85 offset:20480
	s_waitcnt lgkmcnt(0)
	v_mfma_f32_32x32x16_bf16 v[48:63], v[88:91], v[92:95], v[48:63]
	v_mfma_f32_32x32x16_bf16 v[32:47], v[88:91], v[96:99], v[32:47]
	ds_read_b128 v[88:91], v84 offset:4096
	s_waitcnt lgkmcnt(0)
	v_mfma_f32_32x32x16_bf16 v[16:31], v[88:91], v[92:95], v[16:31]
	v_mfma_f32_32x32x16_bf16 v[0:15], v[88:91], v[96:99], v[0:15]
	ds_read_b128 v[88:91], v86
	ds_read_b128 v[92:95], v87 offset:16384
	ds_read_b128 v[96:99], v87 offset:20480
	ds_read_b128 v[120:123], v86 offset:4096
	s_waitcnt vmcnt(0)
	s_waitcnt vmcnt(0) lgkmcnt(0)
	s_barrier
	v_mfma_f32_32x32x16_bf16 v[48:63], v[88:91], v[92:95], v[48:63]
	v_mfma_f32_32x32x16_bf16 v[32:47], v[88:91], v[96:99], v[32:47]
	v_mfma_f32_32x32x16_bf16 v[16:31], v[120:123], v[92:95], v[16:31]
	v_mfma_f32_32x32x16_bf16 v[0:15], v[120:123], v[96:99], v[0:15]
	ds_read_b128 v[88:91], v80 offset:32768
	ds_read_b128 v[92:95], v82 offset:49152
	ds_read_b128 v[96:99], v82 offset:53248
	v_lshl_add_u64 v[116:117], v[64:65], 0, s[60:61]
	global_load_lds_dwordx4 v[116:117], off
	v_lshl_add_u64 v[118:119], v[66:67], 0, s[60:61]
	s_mov_b32 m0, s28
	s_nop 0
	global_load_lds_dwordx4 v[118:119], off
	v_lshl_add_u64 v[116:117], v[68:69], 0, s[60:61]
	s_mov_b32 m0, s29
	s_nop 0
	global_load_lds_dwordx4 v[116:117], off
	v_lshl_add_u64 v[118:119], v[70:71], 0, s[60:61]
	s_mov_b32 m0, s40
	s_nop 0
	global_load_lds_dwordx4 v[118:119], off
	v_lshl_add_u64 v[116:117], v[72:73], 0, s[60:61]
	s_mov_b32 m0, s41
	s_nop 0
	global_load_lds_dwordx4 v[116:117], off
	v_lshl_add_u64 v[118:119], v[74:75], 0, s[60:61]
	s_mov_b32 m0, s42
	s_nop 0
	global_load_lds_dwordx4 v[118:119], off
	v_lshl_add_u64 v[116:117], v[76:77], 0, s[60:61]
	s_mov_b32 m0, s43
	s_nop 0
	global_load_lds_dwordx4 v[116:117], off
	v_lshl_add_u64 v[118:119], v[78:79], 0, s[60:61]
	s_mov_b32 m0, s44
	s_nop 0
	global_load_lds_dwordx4 v[118:119], off
	s_waitcnt lgkmcnt(0)
	v_mfma_f32_32x32x16_bf16 v[48:63], v[88:91], v[92:95], v[48:63]
	s_mov_b32 m0, s20
	v_mfma_f32_32x32x16_bf16 v[32:47], v[88:91], v[96:99], v[32:47]
	ds_read_b128 v[88:91], v80 offset:36864
	s_waitcnt lgkmcnt(0)
	v_mfma_f32_32x32x16_bf16 v[16:31], v[88:91], v[92:95], v[16:31]
	v_mfma_f32_32x32x16_bf16 v[0:15], v[88:91], v[96:99], v[0:15]
	ds_read_b128 v[88:91], v81 offset:32768
	ds_read_b128 v[92:95], v83 offset:49152
	ds_read_b128 v[96:99], v83 offset:53248
	s_waitcnt lgkmcnt(0)
	v_mfma_f32_32x32x16_bf16 v[48:63], v[88:91], v[92:95], v[48:63]
	v_mfma_f32_32x32x16_bf16 v[32:47], v[88:91], v[96:99], v[32:47]
	ds_read_b128 v[88:91], v81 offset:36864
	s_waitcnt lgkmcnt(0)
	v_mfma_f32_32x32x16_bf16 v[16:31], v[88:91], v[92:95], v[16:31]
	v_mfma_f32_32x32x16_bf16 v[0:15], v[88:91], v[96:99], v[0:15]
	ds_read_b128 v[88:91], v84 offset:32768
	ds_read_b128 v[92:95], v85 offset:49152
	ds_read_b128 v[96:99], v85 offset:53248
	s_waitcnt lgkmcnt(0)
	v_mfma_f32_32x32x16_bf16 v[48:63], v[88:91], v[92:95], v[48:63]
	v_mfma_f32_32x32x16_bf16 v[32:47], v[88:91], v[96:99], v[32:47]
	ds_read_b128 v[88:91], v84 offset:36864
	s_waitcnt lgkmcnt(0)
	v_mfma_f32_32x32x16_bf16 v[16:31], v[88:91], v[92:95], v[16:31]
	v_mfma_f32_32x32x16_bf16 v[0:15], v[88:91], v[96:99], v[0:15]
	ds_read_b128 v[88:91], v86 offset:32768
	ds_read_b128 v[92:95], v87 offset:49152
	ds_read_b128 v[96:99], v87 offset:53248
	ds_read_b128 v[120:123], v86 offset:36864
	s_waitcnt vmcnt(0)
	s_waitcnt vmcnt(0) lgkmcnt(0)
	s_barrier
; #define WAIT_V0() asm volatile("s_waitcnt vmcnt(0)" ::: "memory")
; DI void gemm_core(char* smem, int nk, const char* Ab, const char* Bb, const unsigned (&aoff)[4], const unsigned (&boff)[4],
;                   f32x16 (&acc)[2][2]) {
;     ...
;   auto stage = [&](int buf, int kt) __attribute__((always_inline)) {
;     const char* ak = Ab + kt * 128;
;     const char* bk = Bb + kt * 128;
;     char* sa = smem + buf * STAGE_B + w * 4096;
; #pragma unroll
;     for (int i = 0; i < 4; ++i) {
;       __builtin_amdgcn_global_load_lds((const unsigned*)(ak + aoff[i]), (unsigned*)(sa + i * 1024), 16, 0, 0);
;       __builtin_amdgcn_global_load_lds((const unsigned*)(bk + boff[i]), (unsigned*)(sa + 16384 + i * 1024), 16, 0, 0);
;     }
;   };
;   stage(0, 0);
;   WAIT_V0();
;   __syncthreads();
;   for (int kt = 0; kt < nk; ++kt) {
;     const int cur = kt & 1;
;     if (kt + 1 < nk) stage(cur ^ 1, kt + 1);
;     const char* sb = smem + cur * STAGE_B;
; #pragma unroll
;     for (int ks = 0; ks < 4; ++ks) {
;       bf16x8 af[2], bfr[2];
; #pragma unroll
;       for (int mb = 0; mb < 2; ++mb) af[mb] = *(const bf16x8*)(sb + a_base + mb * 4096 + xo[ks]);
; #pragma unroll
;       for (int nb = 0; nb < 2; ++nb) bfr[nb] = *(const bf16x8*)(sb + b_base + nb * 4096 + xo[ks]);
; #pragma unroll
;       for (int mb = 0; mb < 2; ++mb)
; #pragma unroll
;         for (int nb = 0; nb < 2; ++nb)
;           acc[mb][nb] = __builtin_amdgcn_mfma_f32_32x32x16_bf16(af[mb], bfr[nb], acc[mb][nb], 0, 0, 0);
;     }
;     WAIT_V0();
;     __syncthreads();
;   }
	v_mfma_f32_32x32x16_bf16 v[48:63], v[88:91], v[92:95], v[48:63]
	v_mfma_f32_32x32x16_bf16 v[32:47], v[88:91], v[96:99], v[32:47]
	v_mfma_f32_32x32x16_bf16 v[16:31], v[120:123], v[92:95], v[16:31]
	v_mfma_f32_32x32x16_bf16 v[0:15], v[120:123], v[96:99], v[0:15]
	ds_read_b128 v[88:91], v80
	ds_read_b128 v[92:95], v82 offset:16384
	ds_read_b128 v[96:99], v82 offset:20480
	v_lshl_add_u64 v[116:117], v[64:65], 0, s[62:63]
	global_load_lds_dwordx4 v[116:117], off
	v_lshl_add_u64 v[118:119], v[66:67], 0, s[62:63]
	s_mov_b32 m0, s21
	s_nop 0
	global_load_lds_dwordx4 v[118:119], off
	v_lshl_add_u64 v[116:117], v[68:69], 0, s[62:63]
	s_mov_b32 m0, s22
	s_nop 0
	global_load_lds_dwordx4 v[116:117], off
	v_lshl_add_u64 v[118:119], v[70:71], 0, s[62:63]
	s_mov_b32 m0, s1
	s_nop 0
	global_load_lds_dwordx4 v[118:119], off
	v_lshl_add_u64 v[116:117], v[72:73], 0, s[62:63]
	s_mov_b32 m0, s16
	s_nop 0
	global_load_lds_dwordx4 v[116:117], off
	v_lshl_add_u64 v[118:119], v[74:75], 0, s[62:63]
	s_mov_b32 m0, s17
	s_nop 0
	global_load_lds_dwordx4 v[118:119], off
	v_lshl_add_u64 v[116:117], v[76:77], 0, s[62:63]
	s_mov_b32 m0, s18
	s_nop 0
	global_load_lds_dwordx4 v[116:117], off
	v_lshl_add_u64 v[118:119], v[78:79], 0, s[62:63]
	s_mov_b32 m0, s19
	s_nop 0
	global_load_lds_dwordx4 v[118:119], off
	s_waitcnt lgkmcnt(0)
	v_mfma_f32_32x32x16_bf16 v[48:63], v[88:91], v[92:95], v[48:63]
	s_mov_b32 m0, s23
	v_mfma_f32_32x32x16_bf16 v[32:47], v[88:91], v[96:99], v[32:47]
	ds_read_b128 v[88:91], v80 offset:4096
	s_waitcnt lgkmcnt(0)
	v_mfma_f32_32x32x16_bf16 v[16:31], v[88:91], v[92:95], v[16:31]
	v_mfma_f32_32x32x16_bf16 v[0:15], v[88:91], v[96:99], v[0:15]
	ds_read_b128 v[88:91], v81
	ds_read_b128 v[92:95], v83 offset:16384
	ds_read_b128 v[96:99], v83 offset:20480
	s_waitcnt lgkmcnt(0)
	v_mfma_f32_32x32x16_bf16 v[48:63], v[88:91], v[92:95], v[48:63]
	v_mfma_f32_32x32x16_bf16 v[32:47], v[88:91], v[96:99], v[32:47]
	ds_read_b128 v[88:91], v81 offset:4096
	s_waitcnt lgkmcnt(0)
	v_mfma_f32_32x32x16_bf16 v[16:31], v[88:91], v[92:95], v[16:31]
	v_mfma_f32_32x32x16_bf16 v[0:15], v[88:91], v[96:99], v[0:15]
	ds_read_b128 v[88:91], v84
	ds_read_b128 v[92:95], v85 offset:16384
	ds_read_b128 v[96:99], v85 offset:20480
	s_waitcnt lgkmcnt(0)
	v_mfma_f32_32x32x16_bf16 v[48:63], v[88:91], v[92:95], v[48:63]
	v_mfma_f32_32x32x16_bf16 v[32:47], v[88:91], v[96:99], v[32:47]
	ds_read_b128 v[88:91], v84 offset:4096
	s_waitcnt lgkmcnt(0)
	v_mfma_f32_32x32x16_bf16 v[16:31], v[88:91], v[92:95], v[16:31]
	v_mfma_f32_32x32x16_bf16 v[0:15], v[88:91], v[96:99], v[0:15]
	ds_read_b128 v[88:91], v86
	ds_read_b128 v[92:95], v87 offset:16384
	ds_read_b128 v[96:99], v87 offset:20480
	ds_read_b128 v[120:123], v86 offset:4096
	s_waitcnt vmcnt(0)
	s_waitcnt vmcnt(0) lgkmcnt(0)
	s_barrier
	v_mfma_f32_32x32x16_bf16 v[48:63], v[88:91], v[92:95], v[48:63]
	v_mfma_f32_32x32x16_bf16 v[32:47], v[88:91], v[96:99], v[32:47]
	v_mfma_f32_32x32x16_bf16 v[16:31], v[120:123], v[92:95], v[16:31]
	v_mfma_f32_32x32x16_bf16 v[0:15], v[120:123], v[96:99], v[0:15]
	v_lshl_add_u64 v[88:89], v[64:65], 0, s[64:65]
	global_load_lds_dwordx4 v[88:89], off
	v_lshl_add_u64 v[88:89], v[66:67], 0, s[64:65]
	s_mov_b32 m0, s28
	v_lshl_add_u64 v[64:65], v[64:65], 0, s[66:67]
	global_load_lds_dwordx4 v[88:89], off
	v_lshl_add_u64 v[88:89], v[68:69], 0, s[64:65]
	s_mov_b32 m0, s29
	s_nop 0
	global_load_lds_dwordx4 v[88:89], off
	v_lshl_add_u64 v[88:89], v[70:71], 0, s[64:65]
	s_mov_b32 m0, s40
	s_nop 0
	global_load_lds_dwordx4 v[88:89], off
	v_lshl_add_u64 v[88:89], v[72:73], 0, s[64:65]
	s_mov_b32 m0, s41
	s_nop 0
	global_load_lds_dwordx4 v[88:89], off
	v_lshl_add_u64 v[88:89], v[74:75], 0, s[64:65]
	s_mov_b32 m0, s42
	s_nop 0
	global_load_lds_dwordx4 v[88:89], off
	v_lshl_add_u64 v[88:89], v[76:77], 0, s[64:65]
	s_mov_b32 m0, s43
	s_nop 0
	global_load_lds_dwordx4 v[88:89], off
	v_lshl_add_u64 v[88:89], v[78:79], 0, s[64:65]
	s_mov_b32 m0, s44
	s_nop 0
	global_load_lds_dwordx4 v[88:89], off
	ds_read_b128 v[88:91], v80 offset:32768
	ds_read_b128 v[92:95], v82 offset:49152
	ds_read_b128 v[96:99], v82 offset:53248
	s_waitcnt lgkmcnt(0)
	v_mfma_f32_32x32x16_bf16 v[48:63], v[88:91], v[92:95], v[48:63]
	s_mov_b32 m0, s20
	v_mfma_f32_32x32x16_bf16 v[32:47], v[88:91], v[96:99], v[32:47]
	ds_read_b128 v[88:91], v80 offset:36864
	s_waitcnt lgkmcnt(0)
	v_mfma_f32_32x32x16_bf16 v[16:31], v[88:91], v[92:95], v[16:31]
	v_mfma_f32_32x32x16_bf16 v[0:15], v[88:91], v[96:99], v[0:15]
	ds_read_b128 v[88:91], v81 offset:32768
	ds_read_b128 v[92:95], v83 offset:49152
	ds_read_b128 v[96:99], v83 offset:53248
	s_waitcnt lgkmcnt(0)
	v_mfma_f32_32x32x16_bf16 v[48:63], v[88:91], v[92:95], v[48:63]
	v_mfma_f32_32x32x16_bf16 v[32:47], v[88:91], v[96:99], v[32:47]
	ds_read_b128 v[88:91], v81 offset:36864
	s_waitcnt lgkmcnt(0)
	v_mfma_f32_32x32x16_bf16 v[16:31], v[88:91], v[92:95], v[16:31]
	v_mfma_f32_32x32x16_bf16 v[0:15], v[88:91], v[96:99], v[0:15]
	ds_read_b128 v[88:91], v84 offset:32768
	ds_read_b128 v[92:95], v85 offset:49152
	ds_read_b128 v[96:99], v85 offset:53248
	s_waitcnt lgkmcnt(0)
	v_mfma_f32_32x32x16_bf16 v[48:63], v[88:91], v[92:95], v[48:63]
	v_mfma_f32_32x32x16_bf16 v[32:47], v[88:91], v[96:99], v[32:47]
	ds_read_b128 v[88:91], v84 offset:36864
	s_waitcnt lgkmcnt(0)
	v_mfma_f32_32x32x16_bf16 v[16:31], v[88:91], v[92:95], v[16:31]
	v_mfma_f32_32x32x16_bf16 v[0:15], v[88:91], v[96:99], v[0:15]
	ds_read_b128 v[88:91], v86 offset:32768
	ds_read_b128 v[92:95], v87 offset:49152
	ds_read_b128 v[96:99], v87 offset:53248
	s_waitcnt lgkmcnt(0)
	v_mfma_f32_32x32x16_bf16 v[48:63], v[88:91], v[92:95], v[48:63]
	v_mfma_f32_32x32x16_bf16 v[32:47], v[88:91], v[96:99], v[32:47]
	ds_read_b128 v[88:91], v86 offset:36864
	s_waitcnt vmcnt(0)
	s_waitcnt vmcnt(0) lgkmcnt(0)
	s_barrier
; #define WAIT_V0() asm volatile("s_waitcnt vmcnt(0)" ::: "memory")
; DI void gemm_core(char* smem, int nk, const char* Ab, const char* Bb, const unsigned (&aoff)[4], const unsigned (&boff)[4],
;                   f32x16 (&acc)[2][2]) {
;     ...
;   for (int kt = 0; kt < nk; ++kt) {
;     const int cur = kt & 1;
;     if (kt + 1 < nk) stage(cur ^ 1, kt + 1);
;     const char* sb = smem + cur * STAGE_B;
; #pragma unroll
;     for (int ks = 0; ks < 4; ++ks) {
;       bf16x8 af[2], bfr[2];
; #pragma unroll
;       for (int mb = 0; mb < 2; ++mb) af[mb] = *(const bf16x8*)(sb + a_base + mb * 4096 + xo[ks]);
; #pragma unroll
;       for (int nb = 0; nb < 2; ++nb) bfr[nb] = *(const bf16x8*)(sb + b_base + nb * 4096 + xo[ks]);
; #pragma unroll
;       for (int mb = 0; mb < 2; ++mb)
; #pragma unroll
;         for (int nb = 0; nb < 2; ++nb)
;           acc[mb][nb] = __builtin_amdgcn_mfma_f32_32x32x16_bf16(af[mb], bfr[nb], acc[mb][nb], 0, 0, 0);
;     }
;     WAIT_V0();
;     __syncthreads();
;   }
; DI void phase_gemm_in(const Params& P, int layer, char* smem) {
;     ...
;     epi_foreach(acc, [&](int row, int col, float v) __attribute__((always_inline)) {
;       const int c = n0 + col;
;       Cs[row * 136 + col] = (c >= C_QI && c < C_CQ) ? f2h(v) : f2bf(v);
;     });
	global_load_lds_dwordx4 v[64:65], off
	v_lshl_add_u64 v[64:65], v[66:67], 0, s[66:67]
	s_mov_b32 m0, s21
	v_mfma_f32_32x32x16_bf16 v[16:31], v[88:91], v[92:95], v[16:31]
	global_load_lds_dwordx4 v[64:65], off
	v_lshl_add_u64 v[64:65], v[68:69], 0, s[66:67]
	s_mov_b32 m0, s22
	s_nop 0
	global_load_lds_dwordx4 v[64:65], off
	v_lshl_add_u64 v[64:65], v[70:71], 0, s[66:67]
	s_mov_b32 m0, s1
	v_mfma_f32_32x32x16_bf16 v[0:15], v[88:91], v[96:99], v[0:15]
	global_load_lds_dwordx4 v[64:65], off
	v_lshl_add_u64 v[64:65], v[72:73], 0, s[66:67]
	s_mov_b32 m0, s16
	v_mov_b32_e32 v96, v161
	global_load_lds_dwordx4 v[64:65], off
	v_lshl_add_u64 v[64:65], v[74:75], 0, s[66:67]
	s_mov_b32 m0, s17
	v_mov_b32_e32 v97, v161
	global_load_lds_dwordx4 v[64:65], off
	v_lshl_add_u64 v[64:65], v[76:77], 0, s[66:67]
	s_mov_b32 m0, s18
	s_add_i32 s1, s10, 0xfffffa00
	global_load_lds_dwordx4 v[64:65], off
	v_lshl_add_u64 v[64:65], v[78:79], 0, s[66:67]
	s_mov_b32 m0, s19
	s_nop 0
	global_load_lds_dwordx4 v[64:65], off
	ds_read_b128 v[64:67], v80
	ds_read_b128 v[68:71], v82 offset:16384
	ds_read_b128 v[72:75], v82 offset:20480
	s_waitcnt lgkmcnt(0)
	v_mfma_f32_32x32x16_bf16 v[48:63], v[64:67], v[68:71], v[48:63]
	v_mfma_f32_32x32x16_bf16 v[32:47], v[64:67], v[72:75], v[32:47]
	ds_read_b128 v[64:67], v80 offset:4096
	s_waitcnt lgkmcnt(0)
	v_mfma_f32_32x32x16_bf16 v[16:31], v[64:67], v[68:71], v[16:31]
	v_mfma_f32_32x32x16_bf16 v[0:15], v[64:67], v[72:75], v[0:15]
	ds_read_b128 v[64:67], v81
	ds_read_b128 v[68:71], v83 offset:16384
	ds_read_b128 v[72:75], v83 offset:20480
	s_waitcnt lgkmcnt(0)
	v_mfma_f32_32x32x16_bf16 v[48:63], v[64:67], v[68:71], v[48:63]
	v_mfma_f32_32x32x16_bf16 v[32:47], v[64:67], v[72:75], v[32:47]
	ds_read_b128 v[64:67], v81 offset:4096
	s_waitcnt lgkmcnt(0)
	v_mfma_f32_32x32x16_bf16 v[16:31], v[64:67], v[68:71], v[16:31]
	v_mfma_f32_32x32x16_bf16 v[0:15], v[64:67], v[72:75], v[0:15]
	ds_read_b128 v[64:67], v84
	ds_read_b128 v[68:71], v85 offset:16384
	ds_read_b128 v[72:75], v85 offset:20480
	s_waitcnt lgkmcnt(0)
	v_mfma_f32_32x32x16_bf16 v[48:63], v[64:67], v[68:71], v[48:63]
	v_mfma_f32_32x32x16_bf16 v[32:47], v[64:67], v[72:75], v[32:47]
	ds_read_b128 v[64:67], v84 offset:4096
	s_waitcnt lgkmcnt(0)
	v_mfma_f32_32x32x16_bf16 v[16:31], v[64:67], v[68:71], v[16:31]
	v_mfma_f32_32x32x16_bf16 v[0:15], v[64:67], v[72:75], v[0:15]
	ds_read_b128 v[64:67], v86
	ds_read_b128 v[68:71], v87 offset:16384
	ds_read_b128 v[72:75], v87 offset:20480
	ds_read_b128 v[120:123], v86 offset:4096
	s_waitcnt vmcnt(0)
	s_waitcnt vmcnt(0) lgkmcnt(0)
	s_barrier
	v_mfma_f32_32x32x16_bf16 v[48:63], v[64:67], v[68:71], v[48:63]
	v_mfma_f32_32x32x16_bf16 v[32:47], v[64:67], v[72:75], v[32:47]
	v_mfma_f32_32x32x16_bf16 v[16:31], v[120:123], v[68:71], v[16:31]
	v_mfma_f32_32x32x16_bf16 v[0:15], v[120:123], v[72:75], v[0:15]
	ds_read_b128 v[64:67], v80 offset:32768
	ds_read_b128 v[68:71], v82 offset:49152
	ds_read_b128 v[72:75], v82 offset:53248
	s_waitcnt lgkmcnt(1)
	v_mfma_f32_32x32x16_bf16 v[48:63], v[64:67], v[68:71], v[48:63]
	s_waitcnt lgkmcnt(0)
	v_mfma_f32_32x32x16_bf16 v[32:47], v[64:67], v[72:75], v[32:47]
	ds_read_b128 v[64:67], v80 offset:36864
	s_waitcnt lgkmcnt(0)
	v_mfma_f32_32x32x16_bf16 v[16:31], v[64:67], v[68:71], v[16:31]
	v_mfma_f32_32x32x16_bf16 v[0:15], v[64:67], v[72:75], v[0:15]
	ds_read_b128 v[64:67], v81 offset:32768
	ds_read_b128 v[68:71], v83 offset:49152
	ds_read_b128 v[72:75], v83 offset:53248
	s_waitcnt lgkmcnt(1)
	v_mfma_f32_32x32x16_bf16 v[48:63], v[64:67], v[68:71], v[48:63]
	s_waitcnt lgkmcnt(0)
	v_mfma_f32_32x32x16_bf16 v[32:47], v[64:67], v[72:75], v[32:47]
	ds_read_b128 v[64:67], v81 offset:36864
	s_waitcnt lgkmcnt(0)
	v_mfma_f32_32x32x16_bf16 v[16:31], v[64:67], v[68:71], v[16:31]
	ds_read_b128 v[68:71], v84 offset:32768
	ds_read_b128 v[76:79], v84 offset:36864
	v_mfma_f32_32x32x16_bf16 v[0:15], v[64:67], v[72:75], v[0:15]
	ds_read_b128 v[64:67], v85 offset:49152
	ds_read_b128 v[72:75], v85 offset:53248
	ds_read_b128 v[80:83], v86 offset:32768
	ds_read_b128 v[88:91], v86 offset:36864
	ds_read_b128 v[92:95], v87 offset:49152
	ds_read_b128 v[84:87], v87 offset:53248
	s_waitcnt vmcnt(0)
	s_waitcnt lgkmcnt(0)
	s_barrier
	v_mfma_f32_32x32x16_bf16 v[48:63], v[68:71], v[64:67], v[48:63]
	v_mfma_f32_32x32x16_bf16 v[48:63], v[80:83], v[92:95], v[48:63]
	v_mfma_f32_32x32x16_bf16 v[32:47], v[68:71], v[72:75], v[32:47]
	v_lshrrev_b32_e32 v69, 3, v96
	v_lshrrev_b32_e32 v68, 1, v97
	v_and_b32_e32 v69, 4, v69
	v_and_b32_e32 v70, 31, v96
	v_and_or_b32 v68, v68, s7, v69
	s_nop 5
	v_cvt_f16_f32_e32 v69, v48
	v_and_or_b32 v70, v97, 64, v70
	v_or_b32_e32 v71, s1, v70
	v_cmp_gt_u32_e64 s[40:41], s45, v71
	v_cvt_pk_bf16_f32 v48, v48, s0
	v_mfma_f32_32x32x16_bf16 v[16:31], v[76:79], v[64:67], v[16:31]
	v_cndmask_b32_e64 v69, v48, v69, s[40:41]
	v_mul_lo_u32 v48, v68, s97
	v_cvt_f16_f32_e32 v68, v49
	v_cvt_pk_bf16_f32 v49, v49, s0
	v_lshl_add_u32 v48, v70, 1, v48
	v_cvt_f16_f32_e32 v64, v51
	v_cndmask_b32_e64 v49, v49, v68, s[40:41]
	ds_write_b16 v48, v49 offset:272
	v_cvt_f16_f32_e32 v49, v50
	v_cvt_pk_bf16_f32 v50, v50, s0
	v_mfma_f32_32x32x16_bf16 v[0:15], v[76:79], v[72:75], v[0:15]
	ds_write_b16 v48, v69
	v_cndmask_b32_e64 v49, v50, v49, s[40:41]
	ds_write_b16 v48, v49 offset:544
	v_cvt_pk_bf16_f32 v49, v51, s0
	v_cndmask_b32_e64 v49, v49, v64, s[40:41]
	ds_write_b16 v48, v49 offset:816
	v_cvt_f16_f32_e32 v49, v52
	v_cvt_f16_f32_e32 v51, v53
	v_cvt_pk_bf16_f32 v50, v52, s0
	v_mfma_f32_32x32x16_bf16 v[32:47], v[80:83], v[84:87], v[32:47]
	v_cndmask_b32_e64 v49, v50, v49, s[40:41]
	v_cvt_f16_f32_e32 v50, v54
	ds_write_b16 v48, v49 offset:2176
; template <class F>
; DI void epi_foreach(const f32x16 (&acc)[2][2], F f) {
;     ...
;   for (int mb = 0; mb < 2; ++mb)
; #pragma unroll
;     for (int nb = 0; nb < 2; ++nb)
; #pragma unroll
;       for (int r = 0; r < 16; ++r) {
;         const int row = wm * 64 + mb * 32 + (r & 3) + 8 * (r >> 2) + 4 * (lane >> 5);
;         const int col = wn * 64 + nb * 32 + (lane & 31);
;         f(row, col, acc[mb][nb][r]);
;         if ((r & 7) == 7) __builtin_amdgcn_sched_barrier(0);
; DI void phase_gemm_in(const Params& P, int layer, char* smem) {
;     ...
;     epi_foreach(acc, [&](int row, int col, float v) __attribute__((always_inline)) {
;       const int c = n0 + col;
;       Cs[row * 136 + col] = (c >= C_QI && c < C_CQ) ? f2h(v) : f2bf(v);
;     });
	v_cvt_pk_bf16_f32 v49, v53, s0
	v_cndmask_b32_e64 v49, v49, v51, s[40:41]
	v_cvt_f16_f32_e32 v51, v55
	ds_write_b16 v48, v49 offset:2448
	v_cvt_pk_bf16_f32 v49, v54, s0
	v_cndmask_b32_e64 v49, v49, v50, s[40:41]
	ds_write_b16 v48, v49 offset:2720
	v_cvt_pk_bf16_f32 v49, v55, s0
	v_cndmask_b32_e64 v49, v49, v51, s[40:41]
	v_mfma_f32_32x32x16_bf16 v[16:31], v[88:91], v[92:95], v[16:31]
	ds_write_b16 v48, v49 offset:2992
	v_mfma_f32_32x32x16_bf16 v[0:15], v[88:91], v[84:87], v[0:15]
	v_cvt_f16_f32_e32 v49, v56
	v_cvt_pk_bf16_f32 v50, v56, s0
	v_cndmask_b32_e64 v49, v50, v49, s[40:41]
	ds_write_b16 v48, v49 offset:4352
	v_cvt_f16_f32_e32 v49, v57
	v_cvt_pk_bf16_f32 v50, v57, s0
	v_cndmask_b32_e64 v49, v50, v49, s[40:41]
	ds_write_b16 v48, v49 offset:4624
	v_cvt_f16_f32_e32 v49, v58
	v_cvt_pk_bf16_f32 v50, v58, s0
	v_cndmask_b32_e64 v49, v50, v49, s[40:41]
	ds_write_b16 v48, v49 offset:4896
	v_cvt_f16_f32_e32 v49, v59
	v_cvt_pk_bf16_f32 v50, v59, s0
	v_cndmask_b32_e64 v49, v50, v49, s[40:41]
	ds_write_b16 v48, v49 offset:5168
	v_cvt_f16_f32_e32 v49, v60
	v_cvt_pk_bf16_f32 v50, v60, s0
	v_cndmask_b32_e64 v49, v50, v49, s[40:41]
	ds_write_b16 v48, v49 offset:6528
	v_cvt_f16_f32_e32 v49, v61
	v_cvt_pk_bf16_f32 v50, v61, s0
	v_cndmask_b32_e64 v49, v50, v49, s[40:41]
	ds_write_b16 v48, v49 offset:6800
	v_cvt_f16_f32_e32 v49, v62
	v_cvt_pk_bf16_f32 v50, v62, s0
	v_cndmask_b32_e64 v49, v50, v49, s[40:41]
	ds_write_b16 v48, v49 offset:7072
	v_cvt_f16_f32_e32 v49, v63
	v_cvt_pk_bf16_f32 v50, v63, s0
	v_cndmask_b32_e64 v49, v50, v49, s[40:41]
	ds_write_b16 v48, v49 offset:7344
	s_add_i32 s1, s10, 0xfffffa20
	v_or_b32_e32 v49, s1, v70
	v_cmp_gt_u32_e32 vcc, s45, v49
	v_cvt_f16_f32_e32 v49, v32
	v_cvt_pk_bf16_f32 v32, v32, s0
	v_cndmask_b32_e32 v32, v32, v49, vcc
	ds_write_b16 v48, v32 offset:64
	v_cvt_f16_f32_e32 v32, v33
	v_cvt_pk_bf16_f32 v33, v33, s0
	v_cndmask_b32_e32 v32, v33, v32, vcc
	ds_write_b16 v48, v32 offset:336
	v_cvt_f16_f32_e32 v32, v34
	v_cvt_pk_bf16_f32 v33, v34, s0
	v_cndmask_b32_e32 v32, v33, v32, vcc
	ds_write_b16 v48, v32 offset:608
	v_cvt_f16_f32_e32 v32, v35
	v_cvt_pk_bf16_f32 v33, v35, s0
	v_cndmask_b32_e32 v32, v33, v32, vcc
	ds_write_b16 v48, v32 offset:880
	v_cvt_f16_f32_e32 v32, v36
	v_cvt_pk_bf16_f32 v33, v36, s0
	v_cndmask_b32_e32 v32, v33, v32, vcc
	ds_write_b16 v48, v32 offset:2240
	v_cvt_f16_f32_e32 v32, v37
	v_cvt_pk_bf16_f32 v33, v37, s0
	v_cndmask_b32_e32 v32, v33, v32, vcc
	ds_write_b16 v48, v32 offset:2512
	v_cvt_f16_f32_e32 v32, v38
	v_cvt_pk_bf16_f32 v33, v38, s0
	v_cndmask_b32_e32 v32, v33, v32, vcc
	ds_write_b16 v48, v32 offset:2784
	v_cvt_f16_f32_e32 v32, v39
	v_cvt_pk_bf16_f32 v33, v39, s0
	v_cndmask_b32_e32 v32, v33, v32, vcc
	ds_write_b16 v48, v32 offset:3056
	v_cvt_f16_f32_e32 v32, v40
	v_cvt_pk_bf16_f32 v33, v40, s0
	v_cndmask_b32_e32 v32, v33, v32, vcc
	ds_write_b16 v48, v32 offset:4416
	v_cvt_f16_f32_e32 v32, v41
	v_cvt_pk_bf16_f32 v33, v41, s0
	v_cndmask_b32_e32 v32, v33, v32, vcc
	ds_write_b16 v48, v32 offset:4688
	v_cvt_f16_f32_e32 v32, v42
	v_cvt_pk_bf16_f32 v33, v42, s0
	v_cndmask_b32_e32 v32, v33, v32, vcc
	ds_write_b16 v48, v32 offset:4960
	v_cvt_f16_f32_e32 v32, v43
	v_cvt_pk_bf16_f32 v33, v43, s0
	v_cndmask_b32_e32 v32, v33, v32, vcc
	ds_write_b16 v48, v32 offset:5232
	v_cvt_f16_f32_e32 v32, v44
	v_cvt_pk_bf16_f32 v33, v44, s0
	v_cndmask_b32_e32 v32, v33, v32, vcc
	ds_write_b16 v48, v32 offset:6592
	v_cvt_f16_f32_e32 v32, v45
	v_cvt_pk_bf16_f32 v33, v45, s0
	v_cndmask_b32_e32 v32, v33, v32, vcc
	ds_write_b16 v48, v32 offset:6864
	v_cvt_f16_f32_e32 v32, v46
	v_cvt_pk_bf16_f32 v33, v46, s0
	v_cndmask_b32_e32 v32, v33, v32, vcc
	ds_write_b16 v48, v32 offset:7136
	v_cvt_f16_f32_e32 v32, v47
	v_cvt_pk_bf16_f32 v33, v47, s0
	v_cndmask_b32_e32 v32, v33, v32, vcc
	ds_write_b16 v48, v32 offset:7408
	v_cvt_f16_f32_e32 v32, v16
	v_cvt_pk_bf16_f32 v16, v16, s0
	v_cndmask_b32_e64 v16, v16, v32, s[40:41]
	ds_write_b16 v48, v16 offset:8704
	v_cvt_f16_f32_e32 v16, v17
	v_cvt_pk_bf16_f32 v17, v17, s0
	v_cndmask_b32_e64 v16, v17, v16, s[40:41]
	ds_write_b16 v48, v16 offset:8976
	v_cvt_f16_f32_e32 v16, v18
	v_cvt_pk_bf16_f32 v17, v18, s0
	v_cndmask_b32_e64 v16, v17, v16, s[40:41]
	ds_write_b16 v48, v16 offset:9248
	v_cvt_f16_f32_e32 v16, v19
	v_cvt_pk_bf16_f32 v17, v19, s0
	v_cndmask_b32_e64 v16, v17, v16, s[40:41]
	ds_write_b16 v48, v16 offset:9520
	v_cvt_f16_f32_e32 v16, v20
	v_cvt_pk_bf16_f32 v17, v20, s0
	v_cndmask_b32_e64 v16, v17, v16, s[40:41]
	ds_write_b16 v48, v16 offset:10880
	v_cvt_f16_f32_e32 v16, v21
	v_cvt_pk_bf16_f32 v17, v21, s0
	v_cndmask_b32_e64 v16, v17, v16, s[40:41]
	ds_write_b16 v48, v16 offset:11152
	v_cvt_f16_f32_e32 v16, v22
	v_cvt_pk_bf16_f32 v17, v22, s0
	v_cndmask_b32_e64 v16, v17, v16, s[40:41]
	ds_write_b16 v48, v16 offset:11424
	v_cvt_f16_f32_e32 v16, v23
	v_cvt_pk_bf16_f32 v17, v23, s0
	v_cndmask_b32_e64 v16, v17, v16, s[40:41]
	ds_write_b16 v48, v16 offset:11696
	v_cvt_f16_f32_e32 v16, v24
	v_cvt_pk_bf16_f32 v17, v24, s0
	v_cndmask_b32_e64 v16, v17, v16, s[40:41]
	ds_write_b16 v48, v16 offset:13056
	v_cvt_f16_f32_e32 v16, v25
	v_cvt_pk_bf16_f32 v17, v25, s0
	v_cndmask_b32_e64 v16, v17, v16, s[40:41]
	ds_write_b16 v48, v16 offset:13328
	v_cvt_f16_f32_e32 v16, v26
	v_cvt_pk_bf16_f32 v17, v26, s0
	v_cndmask_b32_e64 v16, v17, v16, s[40:41]
; DI int ltid() { int t = threadIdx.x; asm volatile("" : "+v"(t)); return t; }
; DI void store_tile16(const unsigned short* Cs, unsigned short* dst, int ldd) {
;   const int tid = ltid();
; #pragma unroll
;   for (int i = 0; i < 8; ++i) {
;     const int idx = tid + 256 * i;
;     const int row = idx >> 4, c8 = (idx & 15) * 8;
;     *(u32x4*)(dst + (size_t)row * ldd + c8) = *(const u32x4*)(Cs + row * 136 + c8);
;   }
; }
; DI void phase_gemm_in(const Params& P, int layer, char* smem) {
;     ...
;     epi_foreach(acc, [&](int row, int col, float v) __attribute__((always_inline)) {
;       const int c = n0 + col;
;       Cs[row * 136 + col] = (c >= C_QI && c < C_CQ) ? f2h(v) : f2bf(v);
;     });
;     __syncthreads();
;     store_tile16(Cs, Z + (size_t)m0 * ZLD + n0, ZLD);
;     __syncthreads();
	ds_write_b16 v48, v16 offset:13600
	v_cvt_f16_f32_e32 v16, v27
	v_cvt_pk_bf16_f32 v17, v27, s0
	v_cndmask_b32_e64 v16, v17, v16, s[40:41]
	ds_write_b16 v48, v16 offset:13872
	v_cvt_f16_f32_e32 v16, v28
	v_cvt_pk_bf16_f32 v17, v28, s0
	v_cndmask_b32_e64 v16, v17, v16, s[40:41]
	ds_write_b16 v48, v16 offset:15232
	v_cvt_f16_f32_e32 v16, v29
	v_cvt_pk_bf16_f32 v17, v29, s0
	v_cndmask_b32_e64 v16, v17, v16, s[40:41]
	ds_write_b16 v48, v16 offset:15504
	v_cvt_f16_f32_e32 v16, v30
	v_cvt_pk_bf16_f32 v17, v30, s0
	v_cndmask_b32_e64 v16, v17, v16, s[40:41]
	ds_write_b16 v48, v16 offset:15776
	v_cvt_f16_f32_e32 v16, v31
	v_cvt_pk_bf16_f32 v17, v31, s0
	v_cndmask_b32_e64 v16, v17, v16, s[40:41]
	ds_write_b16 v48, v16 offset:16048
	v_cvt_f16_f32_e32 v16, v0
	v_cvt_pk_bf16_f32 v0, v0, s0
	v_cndmask_b32_e32 v0, v0, v16, vcc
	ds_write_b16 v48, v0 offset:8768
	v_cvt_f16_f32_e32 v0, v1
	v_cvt_pk_bf16_f32 v1, v1, s0
	v_cndmask_b32_e32 v0, v1, v0, vcc
	ds_write_b16 v48, v0 offset:9040
	v_cvt_f16_f32_e32 v0, v2
	v_cvt_pk_bf16_f32 v1, v2, s0
	v_cndmask_b32_e32 v0, v1, v0, vcc
	ds_write_b16 v48, v0 offset:9312
	v_cvt_f16_f32_e32 v0, v3
	v_cvt_pk_bf16_f32 v1, v3, s0
	v_cndmask_b32_e32 v0, v1, v0, vcc
	ds_write_b16 v48, v0 offset:9584
	v_cvt_f16_f32_e32 v0, v4
	v_cvt_pk_bf16_f32 v1, v4, s0
	v_cndmask_b32_e32 v0, v1, v0, vcc
	ds_write_b16 v48, v0 offset:10944
	v_cvt_f16_f32_e32 v0, v5
	v_cvt_pk_bf16_f32 v1, v5, s0
	v_cndmask_b32_e32 v0, v1, v0, vcc
	ds_write_b16 v48, v0 offset:11216
	v_cvt_f16_f32_e32 v0, v6
	v_cvt_pk_bf16_f32 v1, v6, s0
	v_cndmask_b32_e32 v0, v1, v0, vcc
	ds_write_b16 v48, v0 offset:11488
	v_cvt_f16_f32_e32 v0, v7
	v_cvt_pk_bf16_f32 v1, v7, s0
	v_cndmask_b32_e32 v0, v1, v0, vcc
	ds_write_b16 v48, v0 offset:11760
	v_cvt_f16_f32_e32 v0, v8
	v_cvt_pk_bf16_f32 v1, v8, s0
	v_cndmask_b32_e32 v0, v1, v0, vcc
	ds_write_b16 v48, v0 offset:13120
	v_cvt_f16_f32_e32 v0, v9
	v_cvt_pk_bf16_f32 v1, v9, s0
	v_cndmask_b32_e32 v0, v1, v0, vcc
	ds_write_b16 v48, v0 offset:13392
	v_cvt_f16_f32_e32 v0, v10
	v_cvt_pk_bf16_f32 v1, v10, s0
	v_cndmask_b32_e32 v0, v1, v0, vcc
	ds_write_b16 v48, v0 offset:13664
	v_cvt_f16_f32_e32 v0, v11
	v_cvt_pk_bf16_f32 v1, v11, s0
	v_cndmask_b32_e32 v0, v1, v0, vcc
	ds_write_b16 v48, v0 offset:13936
	v_cvt_f16_f32_e32 v0, v12
	v_cvt_pk_bf16_f32 v1, v12, s0
	v_cndmask_b32_e32 v0, v1, v0, vcc
	ds_write_b16 v48, v0 offset:15296
	v_cvt_f16_f32_e32 v0, v13
	v_cvt_pk_bf16_f32 v1, v13, s0
	v_cndmask_b32_e32 v0, v1, v0, vcc
	ds_write_b16 v48, v0 offset:15568
	v_cvt_f16_f32_e32 v0, v14
	v_cvt_pk_bf16_f32 v1, v14, s0
	v_cndmask_b32_e32 v0, v1, v0, vcc
	ds_write_b16 v48, v0 offset:15840
	v_cvt_f16_f32_e32 v0, v15
	v_cvt_pk_bf16_f32 v1, v15, s0
	v_cndmask_b32_e32 v0, v1, v0, vcc
	ds_write_b16 v48, v0 offset:16112
	s_mul_i32 s15, s15, 0xb0000
	s_mul_hi_i32 s0, s0, 0x1600
	s_add_u32 s15, s86, s15
	s_addc_u32 s16, s87, s0
	s_lshl_b64 s[0:1], s[10:11], 1
	v_mov_b32_e32 v8, v161
	s_waitcnt lgkmcnt(0)
	s_barrier
	s_add_u32 s0, s15, s0
	s_addc_u32 s1, s16, s1
	v_lshlrev_b32_e32 v0, 4, v8
	v_and_b32_e32 v136, 0xf0, v0
	v_ashrrev_i32_e32 v6, 4, v8
	v_lshl_add_u64 v[4:5], s[0:1], 0, v[136:137]
	v_mad_u64_u32 v[16:17], s[0:1], v6, s97, v[136:137]
	ds_read_b128 v[124:127], v16
	v_mad_i64_i32 v[48:49], s[0:1], v6, s33, v[4:5]
	v_add_u32_e32 v33, 0x100, v8
	v_ashrrev_i32_e32 v41, 4, v33
	v_mad_u64_u32 v[18:19], s[0:1], v41, s97, v[136:137]
	ds_read_b128 v[128:131], v18
	v_mad_i64_i32 v[50:51], s[0:1], v41, s33, v[4:5]
	v_add_u32_e32 v34, 0x200, v8
	v_ashrrev_i32_e32 v42, 4, v34
	v_mad_u64_u32 v[20:21], s[0:1], v42, s97, v[136:137]
	ds_read_b128 v[132:135], v20
	v_mad_i64_i32 v[52:53], s[0:1], v42, s33, v[4:5]
	v_add_u32_e32 v35, 0x300, v8
	v_ashrrev_i32_e32 v43, 4, v35
	v_mad_u64_u32 v[22:23], s[0:1], v43, s97, v[136:137]
	ds_read_b128 v[140:143], v22
	v_mad_i64_i32 v[54:55], s[0:1], v43, s33, v[4:5]
	v_add_u32_e32 v36, 0x400, v8
	v_ashrrev_i32_e32 v44, 4, v36
	v_mad_u64_u32 v[24:25], s[0:1], v44, s97, v[136:137]
	ds_read_b128 v[144:147], v24
	v_mad_i64_i32 v[56:57], s[0:1], v44, s33, v[4:5]
	v_add_u32_e32 v37, 0x500, v8
	v_ashrrev_i32_e32 v45, 4, v37
	v_mad_u64_u32 v[26:27], s[0:1], v45, s97, v[136:137]
	ds_read_b128 v[148:151], v26
	v_mad_i64_i32 v[58:59], s[0:1], v45, s33, v[4:5]
	v_add_u32_e32 v38, 0x600, v8
	v_ashrrev_i32_e32 v46, 4, v38
	v_mad_u64_u32 v[28:29], s[0:1], v46, s97, v[136:137]
	ds_read_b128 v[152:155], v28
	v_mad_i64_i32 v[60:61], s[0:1], v46, s33, v[4:5]
	v_add_u32_e32 v39, 0x700, v8
	v_ashrrev_i32_e32 v47, 4, v39
	v_mad_u64_u32 v[30:31], s[0:1], v47, s97, v[136:137]
	ds_read_b128 v[156:159], v30
	v_mad_i64_i32 v[62:63], s[0:1], v47, s33, v[4:5]
	s_add_i32 s14, s14, s70
	s_add_i32 s13, s13, s3
	s_cmpk_gt_i32 s14, 0x15ff
	s_waitcnt lgkmcnt(7)
	global_store_dwordx4 v[48:49], v[124:127], off
	s_waitcnt lgkmcnt(6)
	global_store_dwordx4 v[50:51], v[128:131], off
	s_waitcnt lgkmcnt(5)
	global_store_dwordx4 v[52:53], v[132:135], off
	s_waitcnt lgkmcnt(4)
	global_store_dwordx4 v[54:55], v[140:143], off
	s_waitcnt lgkmcnt(3)
	global_store_dwordx4 v[56:57], v[144:147], off
	s_waitcnt lgkmcnt(2)
	global_store_dwordx4 v[58:59], v[148:151], off
	s_waitcnt lgkmcnt(1)
	global_store_dwordx4 v[60:61], v[152:155], off
	s_waitcnt lgkmcnt(0)
	global_store_dwordx4 v[62:63], v[156:159], off
	s_barrier
	s_cbranch_scc0 .LBB0_436
